# K-loops duplicated per wave half (no in-loop branches): leading half waits for its LDS-DMA retire after its MFMA block instead of before it
# baseline (speedup 1.0000x reference)
.LBB0_168:
	s_ashr_i32 s43, s42, 31
	s_lshl_b64 s[36:37], s[42:43], 20
	s_add_u32 s44, s20, s36
	s_addc_u32 s45, s21, s37
	s_and_b64 s[36:37], s[38:39], exec
	s_cselect_b32 s36, s45, s51
	s_cselect_b32 s37, s44, s50
	s_ashr_i32 s41, s40, 31
	s_lshl_b64 s[46:47], s[40:41], 15
	s_add_u32 s46, s33, s46
	s_addc_u32 s47, s56, s47
	s_and_b64 s[54:55], s[38:39], exec
	s_cselect_b32 s41, s47, s35
	s_cselect_b32 s43, s46, s34
	s_add_u32 s71, s34, 0x2c0000
	s_addc_u32 s76, s35, 0
	s_add_u32 s50, s50, 0x80080
	v_mov_b32_e32 v4, 0
	s_addc_u32 s51, s51, 0
	s_mov_b32 s77, -2
	v_mov_b32_e32 v5, v4
	v_mov_b32_e32 v6, v4
	v_mov_b32_e32 v7, v4
	v_mov_b32_e32 v8, v4
	v_mov_b32_e32 v9, v4
	v_mov_b32_e32 v10, v4
	v_mov_b32_e32 v11, v4
	v_mov_b32_e32 v20, v4
	v_mov_b32_e32 v21, v4
	v_mov_b32_e32 v22, v4
	v_mov_b32_e32 v23, v4
	v_mov_b32_e32 v24, v4
	v_mov_b32_e32 v25, v4
	v_mov_b32_e32 v26, v4
	v_mov_b32_e32 v27, v4
	v_mov_b32_e32 v36, v4
	v_mov_b32_e32 v37, v4
	v_mov_b32_e32 v38, v4
	v_mov_b32_e32 v39, v4
	v_mov_b32_e32 v40, v4
	v_mov_b32_e32 v41, v4
	v_mov_b32_e32 v42, v4
	v_mov_b32_e32 v43, v4
	v_mov_b32_e32 v52, v4
	v_mov_b32_e32 v53, v4
	v_mov_b32_e32 v54, v4
	v_mov_b32_e32 v55, v4
	v_mov_b32_e32 v56, v4
	v_mov_b32_e32 v57, v4
	v_mov_b32_e32 v58, v4
	v_mov_b32_e32 v59, v4
	v_mov_b32_e32 v12, v4
	v_mov_b32_e32 v13, v4
	v_mov_b32_e32 v14, v4
	v_mov_b32_e32 v15, v4
	v_mov_b32_e32 v16, v4
	v_mov_b32_e32 v17, v4
	v_mov_b32_e32 v18, v4
	v_mov_b32_e32 v19, v4
	v_mov_b32_e32 v28, v4
	v_mov_b32_e32 v29, v4
	v_mov_b32_e32 v30, v4
	v_mov_b32_e32 v31, v4
	v_mov_b32_e32 v32, v4
	v_mov_b32_e32 v33, v4
	v_mov_b32_e32 v34, v4
	v_mov_b32_e32 v35, v4
	v_mov_b32_e32 v44, v4
	v_mov_b32_e32 v45, v4
	v_mov_b32_e32 v46, v4
	v_mov_b32_e32 v47, v4
	v_mov_b32_e32 v48, v4
	v_mov_b32_e32 v49, v4
	v_mov_b32_e32 v50, v4
	v_mov_b32_e32 v51, v4
	v_mov_b32_e32 v60, v4
	v_mov_b32_e32 v61, v4
	v_mov_b32_e32 v62, v4
	v_mov_b32_e32 v63, v4
	v_mov_b32_e32 v64, v4
	v_mov_b32_e32 v65, v4
	v_mov_b32_e32 v66, v4
	v_mov_b32_e32 v67, v4
	v_mov_b32_e32 v68, v4
	v_mov_b32_e32 v69, v4
	v_mov_b32_e32 v70, v4
	v_mov_b32_e32 v71, v4
	v_mov_b32_e32 v72, v4
	v_mov_b32_e32 v73, v4
	v_mov_b32_e32 v74, v4
	v_mov_b32_e32 v75, v4
	v_mov_b32_e32 v84, v4
	v_mov_b32_e32 v85, v4
	v_mov_b32_e32 v86, v4
	v_mov_b32_e32 v87, v4
	v_mov_b32_e32 v88, v4
	v_mov_b32_e32 v89, v4
	v_mov_b32_e32 v90, v4
	v_mov_b32_e32 v91, v4
	v_mov_b32_e32 v100, v4
	v_mov_b32_e32 v101, v4
	v_mov_b32_e32 v102, v4
	v_mov_b32_e32 v103, v4
	v_mov_b32_e32 v104, v4
	v_mov_b32_e32 v105, v4
	v_mov_b32_e32 v106, v4
	v_mov_b32_e32 v107, v4
	v_mov_b32_e32 v116, v4
	v_mov_b32_e32 v117, v4
	v_mov_b32_e32 v118, v4
	v_mov_b32_e32 v119, v4
	v_mov_b32_e32 v120, v4
	v_mov_b32_e32 v121, v4
	v_mov_b32_e32 v122, v4
	v_mov_b32_e32 v123, v4
	v_mov_b32_e32 v76, v4
	v_mov_b32_e32 v77, v4
	v_mov_b32_e32 v78, v4
	v_mov_b32_e32 v79, v4
	v_mov_b32_e32 v80, v4
	v_mov_b32_e32 v81, v4
	v_mov_b32_e32 v82, v4
	v_mov_b32_e32 v83, v4
	v_mov_b32_e32 v92, v4
	v_mov_b32_e32 v93, v4
	v_mov_b32_e32 v94, v4
	v_mov_b32_e32 v95, v4
	v_mov_b32_e32 v96, v4
	v_mov_b32_e32 v97, v4
	v_mov_b32_e32 v98, v4
	v_mov_b32_e32 v99, v4
	v_mov_b32_e32 v108, v4
	v_mov_b32_e32 v109, v4
	v_mov_b32_e32 v110, v4
	v_mov_b32_e32 v111, v4
	v_mov_b32_e32 v112, v4
	v_mov_b32_e32 v113, v4
	v_mov_b32_e32 v114, v4
	v_mov_b32_e32 v115, v4
	v_mov_b32_e32 v124, v4
	v_mov_b32_e32 v125, v4
	v_mov_b32_e32 v126, v4
	v_mov_b32_e32 v127, v4
	v_mov_b32_e32 v128, v4
	v_mov_b32_e32 v129, v4
	v_mov_b32_e32 v130, v4
	v_mov_b32_e32 v131, v4
	v_readfirstlane_b32 s101, v156
	s_bfe_u32 s101, s101, 0x10008
	s_cmp_lg_u32 s101, 0
	s_cbranch_scc1 .Ltrail_1
.LBB0_169:
	s_add_u32 s34, s50, 0xfff80080
	s_addc_u32 s35, s51, -1
	s_add_i32 s52, 0, 0x10000
	s_cmp_eq_u32 s77, 28
	s_cselect_b32 s55, s36, s35
	s_cselect_b32 s54, s37, s34
	v_add_u32_e32 v145, s52, v142
	s_cselect_b32 s35, s41, s76
	s_cselect_b32 s34, s43, s71
	s_add_i32 s53, 0, 0x14000
	ds_read_b128 v[146:149], v145
	ds_read_b128 v[150:153], v145 offset:1024
	ds_read_b128 v[172:175], v145 offset:2048
	ds_read_b128 v[176:179], v145 offset:3072
	v_add_u32_e32 v145, s53, v142
	ds_read_b128 v[180:183], v145
	ds_read_b128 v[184:187], v145 offset:1024
	ds_read_b128 v[188:191], v145 offset:2048
	ds_read_b128 v[192:195], v145 offset:3072
	v_lshl_add_u64 v[154:155], s[50:51], 0, v[138:139]
	s_add_i32 m0, s57, 0xc000
	ds_read_b128 v[196:199], v144
	ds_read_b128 v[200:203], v144 offset:1024
	ds_read_b128 v[204:207], v144 offset:2048
	ds_read_b128 v[208:211], v144 offset:3072
	ds_read_b128 v[212:215], v144 offset:4096
	ds_read_b128 v[216:219], v144 offset:5120
	ds_read_b128 v[228:231], v144 offset:6144
	ds_read_b128 v[232:235], v144 offset:7168
	global_load_lds_dwordx4 v[154:155], off
	v_lshl_add_u64 v[154:155], s[50:51], 0, v[140:141]
	s_add_i32 m0, s57, 0xe000
	s_nop 0
	global_load_lds_dwordx4 v[154:155], off
	s_waitcnt lgkmcnt(0)
	s_barrier
	s_setprio 1
	v_mfma_f32_16x16x32_bf16 v[128:131], v[146:149], v[196:199], v[128:131]
	v_mfma_f32_16x16x32_bf16 v[128:131], v[150:153], v[200:203], v[128:131]
	v_mfma_f32_16x16x32_bf16 v[124:127], v[172:175], v[196:199], v[124:127]
	v_mfma_f32_16x16x32_bf16 v[124:127], v[176:179], v[200:203], v[124:127]
	v_mfma_f32_16x16x32_bf16 v[108:111], v[172:175], v[204:207], v[108:111]
	v_mfma_f32_16x16x32_bf16 v[108:111], v[176:179], v[208:211], v[108:111]
	v_mfma_f32_16x16x32_bf16 v[112:115], v[146:149], v[204:207], v[112:115]
	v_mfma_f32_16x16x32_bf16 v[112:115], v[150:153], v[208:211], v[112:115]
	v_mfma_f32_16x16x32_bf16 v[96:99], v[146:149], v[212:215], v[96:99]
	v_mfma_f32_16x16x32_bf16 v[96:99], v[150:153], v[216:219], v[96:99]
	v_mfma_f32_16x16x32_bf16 v[92:95], v[172:175], v[212:215], v[92:95]
	v_mfma_f32_16x16x32_bf16 v[92:95], v[176:179], v[216:219], v[92:95]
	v_mfma_f32_16x16x32_bf16 v[76:79], v[172:175], v[228:231], v[76:79]
	v_mfma_f32_16x16x32_bf16 v[76:79], v[176:179], v[232:235], v[76:79]
	v_mfma_f32_16x16x32_bf16 v[80:83], v[146:149], v[228:231], v[80:83]
	v_mfma_f32_16x16x32_bf16 v[80:83], v[150:153], v[232:235], v[80:83]
	v_mfma_f32_16x16x32_bf16 v[120:123], v[180:183], v[196:199], v[120:123]
	v_mfma_f32_16x16x32_bf16 v[120:123], v[184:187], v[200:203], v[120:123]
	v_mfma_f32_16x16x32_bf16 v[116:119], v[188:191], v[196:199], v[116:119]
	v_mfma_f32_16x16x32_bf16 v[116:119], v[192:195], v[200:203], v[116:119]
	v_mfma_f32_16x16x32_bf16 v[100:103], v[188:191], v[204:207], v[100:103]
	v_mfma_f32_16x16x32_bf16 v[100:103], v[192:195], v[208:211], v[100:103]
	v_mfma_f32_16x16x32_bf16 v[104:107], v[180:183], v[204:207], v[104:107]
	v_mfma_f32_16x16x32_bf16 v[104:107], v[184:187], v[208:211], v[104:107]
	v_mfma_f32_16x16x32_bf16 v[88:91], v[180:183], v[212:215], v[88:91]
	v_mfma_f32_16x16x32_bf16 v[88:91], v[184:187], v[216:219], v[88:91]
	v_mfma_f32_16x16x32_bf16 v[84:87], v[188:191], v[212:215], v[84:87]
	v_mfma_f32_16x16x32_bf16 v[84:87], v[192:195], v[216:219], v[84:87]
	v_mfma_f32_16x16x32_bf16 v[68:71], v[188:191], v[228:231], v[68:71]
	v_mfma_f32_16x16x32_bf16 v[68:71], v[192:195], v[232:235], v[68:71]
	v_mfma_f32_16x16x32_bf16 v[72:75], v[180:183], v[228:231], v[72:75]
	v_mfma_f32_16x16x32_bf16 v[72:75], v[184:187], v[232:235], v[72:75]
	s_setprio 0
	s_waitcnt vmcnt(8)
	s_barrier
	s_add_i32 s52, s52, s19
	v_lshl_add_u64 v[154:155], s[34:35], 0, v[134:135]
	s_mov_b32 m0, s52
	ds_read_b128 v[196:199], v144 offset:16384
	ds_read_b128 v[200:203], v144 offset:17408
	ds_read_b128 v[204:207], v144 offset:18432
	ds_read_b128 v[208:211], v144 offset:19456
	ds_read_b128 v[212:215], v144 offset:20480
	ds_read_b128 v[216:219], v144 offset:21504
	ds_read_b128 v[228:231], v144 offset:22528
	ds_read_b128 v[232:235], v144 offset:23552
	global_load_lds_dwordx4 v[154:155], off
	s_add_i32 m0, s52, 0x2000
	s_add_u32 s96, s34, 0x4000
	v_lshl_add_u64 v[154:155], s[34:35], 0, v[0:1]
	s_addc_u32 s97, s35, 0
	s_add_i32 s52, s53, s19
	global_load_lds_dwordx4 v[154:155], off
	v_lshl_add_u64 v[154:155], s[96:97], 0, v[134:135]
	s_mov_b32 m0, s52
	v_lshl_add_u64 v[236:237], s[54:55], 0, v[132:133]
	global_load_lds_dwordx4 v[154:155], off
	v_lshl_add_u64 v[154:155], s[96:97], 0, v[0:1]
	s_add_i32 m0, s52, 0x2000
	s_nop 0
	global_load_lds_dwordx4 v[154:155], off
	v_lshl_add_u64 v[154:155], s[54:55], 0, v[136:137]
	s_mov_b32 m0, s57
	s_nop 0
	global_load_lds_dwordx4 v[154:155], off
	s_mov_b32 m0, s58
	s_nop 0
	global_load_lds_dwordx4 v[236:237], off
	s_waitcnt lgkmcnt(0)
	s_barrier
	s_setprio 1
	v_mfma_f32_16x16x32_bf16 v[64:67], v[146:149], v[196:199], v[64:67]
	v_mfma_f32_16x16x32_bf16 v[64:67], v[150:153], v[200:203], v[64:67]
	v_mfma_f32_16x16x32_bf16 v[60:63], v[172:175], v[196:199], v[60:63]
	v_mfma_f32_16x16x32_bf16 v[60:63], v[176:179], v[200:203], v[60:63]
	v_mfma_f32_16x16x32_bf16 v[44:47], v[172:175], v[204:207], v[44:47]
	v_mfma_f32_16x16x32_bf16 v[44:47], v[176:179], v[208:211], v[44:47]
	v_mfma_f32_16x16x32_bf16 v[48:51], v[146:149], v[204:207], v[48:51]
	v_mfma_f32_16x16x32_bf16 v[48:51], v[150:153], v[208:211], v[48:51]
	v_mfma_f32_16x16x32_bf16 v[32:35], v[146:149], v[212:215], v[32:35]
	v_mfma_f32_16x16x32_bf16 v[32:35], v[150:153], v[216:219], v[32:35]
	v_mfma_f32_16x16x32_bf16 v[28:31], v[172:175], v[212:215], v[28:31]
	v_mfma_f32_16x16x32_bf16 v[28:31], v[176:179], v[216:219], v[28:31]
	v_mfma_f32_16x16x32_bf16 v[12:15], v[172:175], v[228:231], v[12:15]
	v_mfma_f32_16x16x32_bf16 v[12:15], v[176:179], v[232:235], v[12:15]
	v_mfma_f32_16x16x32_bf16 v[16:19], v[146:149], v[228:231], v[16:19]
	v_mfma_f32_16x16x32_bf16 v[16:19], v[150:153], v[232:235], v[16:19]
	v_mfma_f32_16x16x32_bf16 v[56:59], v[180:183], v[196:199], v[56:59]
	v_mfma_f32_16x16x32_bf16 v[56:59], v[184:187], v[200:203], v[56:59]
	v_mfma_f32_16x16x32_bf16 v[52:55], v[188:191], v[196:199], v[52:55]
	v_mfma_f32_16x16x32_bf16 v[52:55], v[192:195], v[200:203], v[52:55]
	v_mfma_f32_16x16x32_bf16 v[36:39], v[188:191], v[204:207], v[36:39]
	v_mfma_f32_16x16x32_bf16 v[36:39], v[192:195], v[208:211], v[36:39]
	v_mfma_f32_16x16x32_bf16 v[40:43], v[180:183], v[204:207], v[40:43]
	v_mfma_f32_16x16x32_bf16 v[40:43], v[184:187], v[208:211], v[40:43]
	v_mfma_f32_16x16x32_bf16 v[24:27], v[180:183], v[212:215], v[24:27]
	v_mfma_f32_16x16x32_bf16 v[24:27], v[184:187], v[216:219], v[24:27]
	v_mfma_f32_16x16x32_bf16 v[20:23], v[188:191], v[212:215], v[20:23]
	v_mfma_f32_16x16x32_bf16 v[20:23], v[192:195], v[216:219], v[20:23]
	v_mfma_f32_16x16x32_bf16 v[4:7], v[188:191], v[228:231], v[4:7]
	v_mfma_f32_16x16x32_bf16 v[4:7], v[192:195], v[232:235], v[4:7]
	v_mfma_f32_16x16x32_bf16 v[8:11], v[180:183], v[228:231], v[8:11]
	v_mfma_f32_16x16x32_bf16 v[8:11], v[184:187], v[232:235], v[8:11]
	s_setprio 0
	s_waitcnt vmcnt(8)
	s_barrier
	s_add_i32 s52, 0, 0x18000
	v_add_u32_e32 v145, s52, v142
	s_add_i32 s53, 0, 0x1c000
	ds_read_b128 v[146:149], v145
	ds_read_b128 v[150:153], v145 offset:1024
	ds_read_b128 v[172:175], v145 offset:2048
	ds_read_b128 v[176:179], v145 offset:3072
	v_add_u32_e32 v145, s53, v142
	ds_read_b128 v[180:183], v145
	ds_read_b128 v[184:187], v145 offset:1024
	ds_read_b128 v[188:191], v145 offset:2048
	ds_read_b128 v[192:195], v145 offset:3072
	s_add_u32 s54, s54, 0x80000
	s_addc_u32 s55, s55, 0
	s_mov_b32 m0, s59
	v_lshl_add_u64 v[238:239], s[54:55], 0, v[136:137]
	ds_read_b128 v[196:199], v144 offset:32768
	ds_read_b128 v[200:203], v144 offset:33792
	ds_read_b128 v[204:207], v144 offset:34816
	ds_read_b128 v[208:211], v144 offset:35840
	ds_read_b128 v[212:215], v144 offset:36864
	ds_read_b128 v[216:219], v144 offset:37888
	ds_read_b128 v[228:231], v144 offset:38912
	ds_read_b128 v[232:235], v144 offset:39936
	global_load_lds_dwordx4 v[238:239], off
	v_lshl_add_u64 v[238:239], s[54:55], 0, v[132:133]
	s_mov_b32 m0, s60
	s_nop 0
	global_load_lds_dwordx4 v[238:239], off
	s_waitcnt lgkmcnt(0)
	s_barrier
	s_setprio 1
	v_mfma_f32_16x16x32_bf16 v[128:131], v[146:149], v[196:199], v[128:131]
	v_mfma_f32_16x16x32_bf16 v[128:131], v[150:153], v[200:203], v[128:131]
	v_mfma_f32_16x16x32_bf16 v[124:127], v[172:175], v[196:199], v[124:127]
	v_mfma_f32_16x16x32_bf16 v[124:127], v[176:179], v[200:203], v[124:127]
	v_mfma_f32_16x16x32_bf16 v[108:111], v[172:175], v[204:207], v[108:111]
	v_mfma_f32_16x16x32_bf16 v[108:111], v[176:179], v[208:211], v[108:111]
	v_mfma_f32_16x16x32_bf16 v[112:115], v[146:149], v[204:207], v[112:115]
	v_mfma_f32_16x16x32_bf16 v[112:115], v[150:153], v[208:211], v[112:115]
	v_mfma_f32_16x16x32_bf16 v[96:99], v[146:149], v[212:215], v[96:99]
	v_mfma_f32_16x16x32_bf16 v[96:99], v[150:153], v[216:219], v[96:99]
	v_mfma_f32_16x16x32_bf16 v[92:95], v[172:175], v[212:215], v[92:95]
	v_mfma_f32_16x16x32_bf16 v[92:95], v[176:179], v[216:219], v[92:95]
	v_mfma_f32_16x16x32_bf16 v[76:79], v[172:175], v[228:231], v[76:79]
	v_mfma_f32_16x16x32_bf16 v[76:79], v[176:179], v[232:235], v[76:79]
	v_mfma_f32_16x16x32_bf16 v[80:83], v[146:149], v[228:231], v[80:83]
	v_mfma_f32_16x16x32_bf16 v[80:83], v[150:153], v[232:235], v[80:83]
	v_mfma_f32_16x16x32_bf16 v[120:123], v[180:183], v[196:199], v[120:123]
	v_mfma_f32_16x16x32_bf16 v[120:123], v[184:187], v[200:203], v[120:123]
	v_mfma_f32_16x16x32_bf16 v[116:119], v[188:191], v[196:199], v[116:119]
	v_mfma_f32_16x16x32_bf16 v[116:119], v[192:195], v[200:203], v[116:119]
	v_mfma_f32_16x16x32_bf16 v[100:103], v[188:191], v[204:207], v[100:103]
	v_mfma_f32_16x16x32_bf16 v[100:103], v[192:195], v[208:211], v[100:103]
	v_mfma_f32_16x16x32_bf16 v[104:107], v[180:183], v[204:207], v[104:107]
	v_mfma_f32_16x16x32_bf16 v[104:107], v[184:187], v[208:211], v[104:107]
	v_mfma_f32_16x16x32_bf16 v[88:91], v[180:183], v[212:215], v[88:91]
	v_mfma_f32_16x16x32_bf16 v[88:91], v[184:187], v[216:219], v[88:91]
	v_mfma_f32_16x16x32_bf16 v[84:87], v[188:191], v[212:215], v[84:87]
	v_mfma_f32_16x16x32_bf16 v[84:87], v[192:195], v[216:219], v[84:87]
	v_mfma_f32_16x16x32_bf16 v[68:71], v[188:191], v[228:231], v[68:71]
	v_mfma_f32_16x16x32_bf16 v[68:71], v[192:195], v[232:235], v[68:71]
	v_mfma_f32_16x16x32_bf16 v[72:75], v[180:183], v[228:231], v[72:75]
	v_mfma_f32_16x16x32_bf16 v[72:75], v[184:187], v[232:235], v[72:75]
	s_setprio 0
	s_waitcnt vmcnt(8)
	s_barrier
	s_add_u32 s54, s34, 0x160000
	s_addc_u32 s55, s35, 0
	s_add_i32 s52, s52, s19
	v_lshl_add_u64 v[238:239], s[54:55], 0, v[134:135]
	s_mov_b32 m0, s52
	ds_read_b128 v[196:199], v144 offset:49152
	ds_read_b128 v[200:203], v144 offset:50176
	ds_read_b128 v[204:207], v144 offset:51200
	ds_read_b128 v[208:211], v144 offset:52224
	ds_read_b128 v[212:215], v144 offset:53248
	ds_read_b128 v[216:219], v144 offset:54272
	ds_read_b128 v[228:231], v144 offset:55296
	ds_read_b128 v[232:235], v144 offset:56320
	global_load_lds_dwordx4 v[238:239], off
	s_add_i32 m0, s52, 0x2000
	s_add_u32 s34, s34, 0x164000
	v_lshl_add_u64 v[238:239], s[54:55], 0, v[0:1]
	s_addc_u32 s35, s35, 0
	s_add_i32 s52, s53, s19
	global_load_lds_dwordx4 v[238:239], off
	v_lshl_add_u64 v[238:239], s[34:35], 0, v[134:135]
	s_mov_b32 m0, s52
	v_lshl_add_u64 v[154:155], v[154:155], 0, s[14:15]
	global_load_lds_dwordx4 v[238:239], off
	v_lshl_add_u64 v[238:239], s[34:35], 0, v[0:1]
	s_add_i32 m0, s52, 0x2000
	s_nop 0
	global_load_lds_dwordx4 v[238:239], off
	s_mov_b32 m0, s61
	s_nop 0
	global_load_lds_dwordx4 v[154:155], off
	v_lshl_add_u64 v[154:155], v[236:237], 0, s[14:15]
	s_mov_b32 m0, s62
	s_nop 0
	global_load_lds_dwordx4 v[154:155], off
	s_waitcnt lgkmcnt(0)
	s_barrier
	s_setprio 1
	v_mfma_f32_16x16x32_bf16 v[64:67], v[146:149], v[196:199], v[64:67]
	v_mfma_f32_16x16x32_bf16 v[64:67], v[150:153], v[200:203], v[64:67]
	v_mfma_f32_16x16x32_bf16 v[60:63], v[172:175], v[196:199], v[60:63]
	v_mfma_f32_16x16x32_bf16 v[60:63], v[176:179], v[200:203], v[60:63]
	v_mfma_f32_16x16x32_bf16 v[44:47], v[172:175], v[204:207], v[44:47]
	v_mfma_f32_16x16x32_bf16 v[44:47], v[176:179], v[208:211], v[44:47]
	v_mfma_f32_16x16x32_bf16 v[48:51], v[146:149], v[204:207], v[48:51]
	v_mfma_f32_16x16x32_bf16 v[48:51], v[150:153], v[208:211], v[48:51]
	v_mfma_f32_16x16x32_bf16 v[32:35], v[146:149], v[212:215], v[32:35]
	v_mfma_f32_16x16x32_bf16 v[32:35], v[150:153], v[216:219], v[32:35]
	v_mfma_f32_16x16x32_bf16 v[28:31], v[172:175], v[212:215], v[28:31]
	v_mfma_f32_16x16x32_bf16 v[28:31], v[176:179], v[216:219], v[28:31]
	v_mfma_f32_16x16x32_bf16 v[12:15], v[172:175], v[228:231], v[12:15]
	v_mfma_f32_16x16x32_bf16 v[12:15], v[176:179], v[232:235], v[12:15]
	v_mfma_f32_16x16x32_bf16 v[16:19], v[146:149], v[228:231], v[16:19]
	v_mfma_f32_16x16x32_bf16 v[16:19], v[150:153], v[232:235], v[16:19]
	v_mfma_f32_16x16x32_bf16 v[56:59], v[180:183], v[196:199], v[56:59]
	v_mfma_f32_16x16x32_bf16 v[56:59], v[184:187], v[200:203], v[56:59]
	v_mfma_f32_16x16x32_bf16 v[52:55], v[188:191], v[196:199], v[52:55]
	v_mfma_f32_16x16x32_bf16 v[52:55], v[192:195], v[200:203], v[52:55]
	v_mfma_f32_16x16x32_bf16 v[36:39], v[188:191], v[204:207], v[36:39]
	v_mfma_f32_16x16x32_bf16 v[36:39], v[192:195], v[208:211], v[36:39]
	v_mfma_f32_16x16x32_bf16 v[40:43], v[180:183], v[204:207], v[40:43]
	v_mfma_f32_16x16x32_bf16 v[40:43], v[184:187], v[208:211], v[40:43]
	v_mfma_f32_16x16x32_bf16 v[24:27], v[180:183], v[212:215], v[24:27]
	v_mfma_f32_16x16x32_bf16 v[24:27], v[184:187], v[216:219], v[24:27]
	v_mfma_f32_16x16x32_bf16 v[20:23], v[188:191], v[212:215], v[20:23]
	v_mfma_f32_16x16x32_bf16 v[20:23], v[192:195], v[216:219], v[20:23]
	v_mfma_f32_16x16x32_bf16 v[4:7], v[188:191], v[228:231], v[4:7]
	v_mfma_f32_16x16x32_bf16 v[4:7], v[192:195], v[232:235], v[4:7]
	v_mfma_f32_16x16x32_bf16 v[8:11], v[180:183], v[228:231], v[8:11]
	v_mfma_f32_16x16x32_bf16 v[8:11], v[184:187], v[232:235], v[8:11]
	s_setprio 0
	s_waitcnt vmcnt(8)
	s_barrier
	s_add_i32 s77, s77, 2
	s_add_u32 s71, s71, 0x2c0000
	s_addc_u32 s76, s76, 0
	s_add_u32 s50, s50, 0x100
	s_addc_u32 s51, s51, 0
	s_cmp_gt_u32 s77, 29
	s_cbranch_scc0 .LBB0_169
	s_branch .Lkdone_1
.Ltrail_1:
	s_add_u32 s34, s50, 0xfff80080
	s_addc_u32 s35, s51, -1
	s_add_i32 s52, 0, 0x10000
	s_cmp_eq_u32 s77, 28
	s_cselect_b32 s55, s36, s35
	s_cselect_b32 s54, s37, s34
	v_add_u32_e32 v145, s52, v142
	s_cselect_b32 s35, s41, s76
	s_cselect_b32 s34, s43, s71
	s_add_i32 s53, 0, 0x14000
	ds_read_b128 v[146:149], v145
	ds_read_b128 v[150:153], v145 offset:1024
	ds_read_b128 v[172:175], v145 offset:2048
	ds_read_b128 v[176:179], v145 offset:3072
	v_add_u32_e32 v145, s53, v142
	ds_read_b128 v[180:183], v145
	ds_read_b128 v[184:187], v145 offset:1024
	ds_read_b128 v[188:191], v145 offset:2048
	ds_read_b128 v[192:195], v145 offset:3072
	v_lshl_add_u64 v[154:155], s[50:51], 0, v[138:139]
	s_add_i32 m0, s57, 0xc000
	ds_read_b128 v[196:199], v144
	ds_read_b128 v[200:203], v144 offset:1024
	ds_read_b128 v[204:207], v144 offset:2048
	ds_read_b128 v[208:211], v144 offset:3072
	ds_read_b128 v[212:215], v144 offset:4096
	ds_read_b128 v[216:219], v144 offset:5120
	ds_read_b128 v[228:231], v144 offset:6144
	ds_read_b128 v[232:235], v144 offset:7168
	global_load_lds_dwordx4 v[154:155], off
	v_lshl_add_u64 v[154:155], s[50:51], 0, v[140:141]
	s_add_i32 m0, s57, 0xe000
	s_nop 0
	global_load_lds_dwordx4 v[154:155], off
	s_waitcnt vmcnt(8)
	s_waitcnt lgkmcnt(0)
	s_barrier
	s_setprio 1
	v_mfma_f32_16x16x32_bf16 v[128:131], v[146:149], v[196:199], v[128:131]
	v_mfma_f32_16x16x32_bf16 v[128:131], v[150:153], v[200:203], v[128:131]
	v_mfma_f32_16x16x32_bf16 v[124:127], v[172:175], v[196:199], v[124:127]
	v_mfma_f32_16x16x32_bf16 v[124:127], v[176:179], v[200:203], v[124:127]
	v_mfma_f32_16x16x32_bf16 v[108:111], v[172:175], v[204:207], v[108:111]
	v_mfma_f32_16x16x32_bf16 v[108:111], v[176:179], v[208:211], v[108:111]
	v_mfma_f32_16x16x32_bf16 v[112:115], v[146:149], v[204:207], v[112:115]
	v_mfma_f32_16x16x32_bf16 v[112:115], v[150:153], v[208:211], v[112:115]
	v_mfma_f32_16x16x32_bf16 v[96:99], v[146:149], v[212:215], v[96:99]
	v_mfma_f32_16x16x32_bf16 v[96:99], v[150:153], v[216:219], v[96:99]
	v_mfma_f32_16x16x32_bf16 v[92:95], v[172:175], v[212:215], v[92:95]
	v_mfma_f32_16x16x32_bf16 v[92:95], v[176:179], v[216:219], v[92:95]
	v_mfma_f32_16x16x32_bf16 v[76:79], v[172:175], v[228:231], v[76:79]
	v_mfma_f32_16x16x32_bf16 v[76:79], v[176:179], v[232:235], v[76:79]
	v_mfma_f32_16x16x32_bf16 v[80:83], v[146:149], v[228:231], v[80:83]
	v_mfma_f32_16x16x32_bf16 v[80:83], v[150:153], v[232:235], v[80:83]
	v_mfma_f32_16x16x32_bf16 v[120:123], v[180:183], v[196:199], v[120:123]
	v_mfma_f32_16x16x32_bf16 v[120:123], v[184:187], v[200:203], v[120:123]
	v_mfma_f32_16x16x32_bf16 v[116:119], v[188:191], v[196:199], v[116:119]
	v_mfma_f32_16x16x32_bf16 v[116:119], v[192:195], v[200:203], v[116:119]
	v_mfma_f32_16x16x32_bf16 v[100:103], v[188:191], v[204:207], v[100:103]
	v_mfma_f32_16x16x32_bf16 v[100:103], v[192:195], v[208:211], v[100:103]
	v_mfma_f32_16x16x32_bf16 v[104:107], v[180:183], v[204:207], v[104:107]
	v_mfma_f32_16x16x32_bf16 v[104:107], v[184:187], v[208:211], v[104:107]
	v_mfma_f32_16x16x32_bf16 v[88:91], v[180:183], v[212:215], v[88:91]
	v_mfma_f32_16x16x32_bf16 v[88:91], v[184:187], v[216:219], v[88:91]
	v_mfma_f32_16x16x32_bf16 v[84:87], v[188:191], v[212:215], v[84:87]
	v_mfma_f32_16x16x32_bf16 v[84:87], v[192:195], v[216:219], v[84:87]
	v_mfma_f32_16x16x32_bf16 v[68:71], v[188:191], v[228:231], v[68:71]
	v_mfma_f32_16x16x32_bf16 v[68:71], v[192:195], v[232:235], v[68:71]
	v_mfma_f32_16x16x32_bf16 v[72:75], v[180:183], v[228:231], v[72:75]
	v_mfma_f32_16x16x32_bf16 v[72:75], v[184:187], v[232:235], v[72:75]
	s_setprio 0
	s_barrier
	s_add_i32 s52, s52, s19
	v_lshl_add_u64 v[154:155], s[34:35], 0, v[134:135]
	s_mov_b32 m0, s52
	ds_read_b128 v[196:199], v144 offset:16384
	ds_read_b128 v[200:203], v144 offset:17408
	ds_read_b128 v[204:207], v144 offset:18432
	ds_read_b128 v[208:211], v144 offset:19456
	ds_read_b128 v[212:215], v144 offset:20480
	ds_read_b128 v[216:219], v144 offset:21504
	ds_read_b128 v[228:231], v144 offset:22528
	ds_read_b128 v[232:235], v144 offset:23552
	global_load_lds_dwordx4 v[154:155], off
	s_add_i32 m0, s52, 0x2000
	s_add_u32 s96, s34, 0x4000
	v_lshl_add_u64 v[154:155], s[34:35], 0, v[0:1]
	s_addc_u32 s97, s35, 0
	s_add_i32 s52, s53, s19
	global_load_lds_dwordx4 v[154:155], off
	v_lshl_add_u64 v[154:155], s[96:97], 0, v[134:135]
	s_mov_b32 m0, s52
	v_lshl_add_u64 v[236:237], s[54:55], 0, v[132:133]
	global_load_lds_dwordx4 v[154:155], off
	v_lshl_add_u64 v[154:155], s[96:97], 0, v[0:1]
	s_add_i32 m0, s52, 0x2000
	s_nop 0
	global_load_lds_dwordx4 v[154:155], off
	v_lshl_add_u64 v[154:155], s[54:55], 0, v[136:137]
	s_mov_b32 m0, s57
	s_nop 0
	global_load_lds_dwordx4 v[154:155], off
	s_mov_b32 m0, s58
	s_nop 0
	global_load_lds_dwordx4 v[236:237], off
	s_waitcnt vmcnt(8)
	s_waitcnt lgkmcnt(0)
	s_barrier
	s_setprio 1
	v_mfma_f32_16x16x32_bf16 v[64:67], v[146:149], v[196:199], v[64:67]
	v_mfma_f32_16x16x32_bf16 v[64:67], v[150:153], v[200:203], v[64:67]
	v_mfma_f32_16x16x32_bf16 v[60:63], v[172:175], v[196:199], v[60:63]
	v_mfma_f32_16x16x32_bf16 v[60:63], v[176:179], v[200:203], v[60:63]
	v_mfma_f32_16x16x32_bf16 v[44:47], v[172:175], v[204:207], v[44:47]
	v_mfma_f32_16x16x32_bf16 v[44:47], v[176:179], v[208:211], v[44:47]
	v_mfma_f32_16x16x32_bf16 v[48:51], v[146:149], v[204:207], v[48:51]
	v_mfma_f32_16x16x32_bf16 v[48:51], v[150:153], v[208:211], v[48:51]
	v_mfma_f32_16x16x32_bf16 v[32:35], v[146:149], v[212:215], v[32:35]
	v_mfma_f32_16x16x32_bf16 v[32:35], v[150:153], v[216:219], v[32:35]
	v_mfma_f32_16x16x32_bf16 v[28:31], v[172:175], v[212:215], v[28:31]
	v_mfma_f32_16x16x32_bf16 v[28:31], v[176:179], v[216:219], v[28:31]
	v_mfma_f32_16x16x32_bf16 v[12:15], v[172:175], v[228:231], v[12:15]
	v_mfma_f32_16x16x32_bf16 v[12:15], v[176:179], v[232:235], v[12:15]
	v_mfma_f32_16x16x32_bf16 v[16:19], v[146:149], v[228:231], v[16:19]
	v_mfma_f32_16x16x32_bf16 v[16:19], v[150:153], v[232:235], v[16:19]
	v_mfma_f32_16x16x32_bf16 v[56:59], v[180:183], v[196:199], v[56:59]
	v_mfma_f32_16x16x32_bf16 v[56:59], v[184:187], v[200:203], v[56:59]
	v_mfma_f32_16x16x32_bf16 v[52:55], v[188:191], v[196:199], v[52:55]
	v_mfma_f32_16x16x32_bf16 v[52:55], v[192:195], v[200:203], v[52:55]
	v_mfma_f32_16x16x32_bf16 v[36:39], v[188:191], v[204:207], v[36:39]
	v_mfma_f32_16x16x32_bf16 v[36:39], v[192:195], v[208:211], v[36:39]
	v_mfma_f32_16x16x32_bf16 v[40:43], v[180:183], v[204:207], v[40:43]
	v_mfma_f32_16x16x32_bf16 v[40:43], v[184:187], v[208:211], v[40:43]
	v_mfma_f32_16x16x32_bf16 v[24:27], v[180:183], v[212:215], v[24:27]
	v_mfma_f32_16x16x32_bf16 v[24:27], v[184:187], v[216:219], v[24:27]
	v_mfma_f32_16x16x32_bf16 v[20:23], v[188:191], v[212:215], v[20:23]
	v_mfma_f32_16x16x32_bf16 v[20:23], v[192:195], v[216:219], v[20:23]
	v_mfma_f32_16x16x32_bf16 v[4:7], v[188:191], v[228:231], v[4:7]
	v_mfma_f32_16x16x32_bf16 v[4:7], v[192:195], v[232:235], v[4:7]
	v_mfma_f32_16x16x32_bf16 v[8:11], v[180:183], v[228:231], v[8:11]
	v_mfma_f32_16x16x32_bf16 v[8:11], v[184:187], v[232:235], v[8:11]
	s_setprio 0
	s_barrier
	s_add_i32 s52, 0, 0x18000
	v_add_u32_e32 v145, s52, v142
	s_add_i32 s53, 0, 0x1c000
	ds_read_b128 v[146:149], v145
	ds_read_b128 v[150:153], v145 offset:1024
	ds_read_b128 v[172:175], v145 offset:2048
	ds_read_b128 v[176:179], v145 offset:3072
	v_add_u32_e32 v145, s53, v142
	ds_read_b128 v[180:183], v145
	ds_read_b128 v[184:187], v145 offset:1024
	ds_read_b128 v[188:191], v145 offset:2048
	ds_read_b128 v[192:195], v145 offset:3072
	s_add_u32 s54, s54, 0x80000
	s_addc_u32 s55, s55, 0
	s_mov_b32 m0, s59
	v_lshl_add_u64 v[238:239], s[54:55], 0, v[136:137]
	ds_read_b128 v[196:199], v144 offset:32768
	ds_read_b128 v[200:203], v144 offset:33792
	ds_read_b128 v[204:207], v144 offset:34816
	ds_read_b128 v[208:211], v144 offset:35840
	ds_read_b128 v[212:215], v144 offset:36864
	ds_read_b128 v[216:219], v144 offset:37888
	ds_read_b128 v[228:231], v144 offset:38912
	ds_read_b128 v[232:235], v144 offset:39936
	global_load_lds_dwordx4 v[238:239], off
	v_lshl_add_u64 v[238:239], s[54:55], 0, v[132:133]
	s_mov_b32 m0, s60
	s_nop 0
	global_load_lds_dwordx4 v[238:239], off
	s_waitcnt vmcnt(8)
	s_waitcnt lgkmcnt(0)
	s_barrier
	s_setprio 1
	v_mfma_f32_16x16x32_bf16 v[128:131], v[146:149], v[196:199], v[128:131]
	v_mfma_f32_16x16x32_bf16 v[128:131], v[150:153], v[200:203], v[128:131]
	v_mfma_f32_16x16x32_bf16 v[124:127], v[172:175], v[196:199], v[124:127]
	v_mfma_f32_16x16x32_bf16 v[124:127], v[176:179], v[200:203], v[124:127]
	v_mfma_f32_16x16x32_bf16 v[108:111], v[172:175], v[204:207], v[108:111]
	v_mfma_f32_16x16x32_bf16 v[108:111], v[176:179], v[208:211], v[108:111]
	v_mfma_f32_16x16x32_bf16 v[112:115], v[146:149], v[204:207], v[112:115]
	v_mfma_f32_16x16x32_bf16 v[112:115], v[150:153], v[208:211], v[112:115]
	v_mfma_f32_16x16x32_bf16 v[96:99], v[146:149], v[212:215], v[96:99]
	v_mfma_f32_16x16x32_bf16 v[96:99], v[150:153], v[216:219], v[96:99]
	v_mfma_f32_16x16x32_bf16 v[92:95], v[172:175], v[212:215], v[92:95]
	v_mfma_f32_16x16x32_bf16 v[92:95], v[176:179], v[216:219], v[92:95]
	v_mfma_f32_16x16x32_bf16 v[76:79], v[172:175], v[228:231], v[76:79]
	v_mfma_f32_16x16x32_bf16 v[76:79], v[176:179], v[232:235], v[76:79]
	v_mfma_f32_16x16x32_bf16 v[80:83], v[146:149], v[228:231], v[80:83]
	v_mfma_f32_16x16x32_bf16 v[80:83], v[150:153], v[232:235], v[80:83]
	v_mfma_f32_16x16x32_bf16 v[120:123], v[180:183], v[196:199], v[120:123]
	v_mfma_f32_16x16x32_bf16 v[120:123], v[184:187], v[200:203], v[120:123]
	v_mfma_f32_16x16x32_bf16 v[116:119], v[188:191], v[196:199], v[116:119]
	v_mfma_f32_16x16x32_bf16 v[116:119], v[192:195], v[200:203], v[116:119]
	v_mfma_f32_16x16x32_bf16 v[100:103], v[188:191], v[204:207], v[100:103]
	v_mfma_f32_16x16x32_bf16 v[100:103], v[192:195], v[208:211], v[100:103]
	v_mfma_f32_16x16x32_bf16 v[104:107], v[180:183], v[204:207], v[104:107]
	v_mfma_f32_16x16x32_bf16 v[104:107], v[184:187], v[208:211], v[104:107]
	v_mfma_f32_16x16x32_bf16 v[88:91], v[180:183], v[212:215], v[88:91]
	v_mfma_f32_16x16x32_bf16 v[88:91], v[184:187], v[216:219], v[88:91]
	v_mfma_f32_16x16x32_bf16 v[84:87], v[188:191], v[212:215], v[84:87]
	v_mfma_f32_16x16x32_bf16 v[84:87], v[192:195], v[216:219], v[84:87]
	v_mfma_f32_16x16x32_bf16 v[68:71], v[188:191], v[228:231], v[68:71]
	v_mfma_f32_16x16x32_bf16 v[68:71], v[192:195], v[232:235], v[68:71]
	v_mfma_f32_16x16x32_bf16 v[72:75], v[180:183], v[228:231], v[72:75]
	v_mfma_f32_16x16x32_bf16 v[72:75], v[184:187], v[232:235], v[72:75]
	s_setprio 0
	s_barrier
	s_add_u32 s54, s34, 0x160000
	s_addc_u32 s55, s35, 0
	s_add_i32 s52, s52, s19
	v_lshl_add_u64 v[238:239], s[54:55], 0, v[134:135]
	s_mov_b32 m0, s52
	ds_read_b128 v[196:199], v144 offset:49152
	ds_read_b128 v[200:203], v144 offset:50176
	ds_read_b128 v[204:207], v144 offset:51200
	ds_read_b128 v[208:211], v144 offset:52224
	ds_read_b128 v[212:215], v144 offset:53248
	ds_read_b128 v[216:219], v144 offset:54272
	ds_read_b128 v[228:231], v144 offset:55296
	ds_read_b128 v[232:235], v144 offset:56320
	global_load_lds_dwordx4 v[238:239], off
	s_add_i32 m0, s52, 0x2000
	s_add_u32 s34, s34, 0x164000
	v_lshl_add_u64 v[238:239], s[54:55], 0, v[0:1]
	s_addc_u32 s35, s35, 0
	s_add_i32 s52, s53, s19
	global_load_lds_dwordx4 v[238:239], off
	v_lshl_add_u64 v[238:239], s[34:35], 0, v[134:135]
	s_mov_b32 m0, s52
	v_lshl_add_u64 v[154:155], v[154:155], 0, s[14:15]
	global_load_lds_dwordx4 v[238:239], off
	v_lshl_add_u64 v[238:239], s[34:35], 0, v[0:1]
	s_add_i32 m0, s52, 0x2000
	s_nop 0
	global_load_lds_dwordx4 v[238:239], off
	s_mov_b32 m0, s61
	s_nop 0
	global_load_lds_dwordx4 v[154:155], off
	v_lshl_add_u64 v[154:155], v[236:237], 0, s[14:15]
	s_mov_b32 m0, s62
	s_nop 0
	global_load_lds_dwordx4 v[154:155], off
	s_waitcnt vmcnt(8)
	s_waitcnt lgkmcnt(0)
	s_barrier
	s_setprio 1
	v_mfma_f32_16x16x32_bf16 v[64:67], v[146:149], v[196:199], v[64:67]
	v_mfma_f32_16x16x32_bf16 v[64:67], v[150:153], v[200:203], v[64:67]
	v_mfma_f32_16x16x32_bf16 v[60:63], v[172:175], v[196:199], v[60:63]
	v_mfma_f32_16x16x32_bf16 v[60:63], v[176:179], v[200:203], v[60:63]
	v_mfma_f32_16x16x32_bf16 v[44:47], v[172:175], v[204:207], v[44:47]
	v_mfma_f32_16x16x32_bf16 v[44:47], v[176:179], v[208:211], v[44:47]
	v_mfma_f32_16x16x32_bf16 v[48:51], v[146:149], v[204:207], v[48:51]
	v_mfma_f32_16x16x32_bf16 v[48:51], v[150:153], v[208:211], v[48:51]
	v_mfma_f32_16x16x32_bf16 v[32:35], v[146:149], v[212:215], v[32:35]
	v_mfma_f32_16x16x32_bf16 v[32:35], v[150:153], v[216:219], v[32:35]
	v_mfma_f32_16x16x32_bf16 v[28:31], v[172:175], v[212:215], v[28:31]
	v_mfma_f32_16x16x32_bf16 v[28:31], v[176:179], v[216:219], v[28:31]
	v_mfma_f32_16x16x32_bf16 v[12:15], v[172:175], v[228:231], v[12:15]
	v_mfma_f32_16x16x32_bf16 v[12:15], v[176:179], v[232:235], v[12:15]
	v_mfma_f32_16x16x32_bf16 v[16:19], v[146:149], v[228:231], v[16:19]
	v_mfma_f32_16x16x32_bf16 v[16:19], v[150:153], v[232:235], v[16:19]
	v_mfma_f32_16x16x32_bf16 v[56:59], v[180:183], v[196:199], v[56:59]
	v_mfma_f32_16x16x32_bf16 v[56:59], v[184:187], v[200:203], v[56:59]
	v_mfma_f32_16x16x32_bf16 v[52:55], v[188:191], v[196:199], v[52:55]
	v_mfma_f32_16x16x32_bf16 v[52:55], v[192:195], v[200:203], v[52:55]
	v_mfma_f32_16x16x32_bf16 v[36:39], v[188:191], v[204:207], v[36:39]
	v_mfma_f32_16x16x32_bf16 v[36:39], v[192:195], v[208:211], v[36:39]
	v_mfma_f32_16x16x32_bf16 v[40:43], v[180:183], v[204:207], v[40:43]
	v_mfma_f32_16x16x32_bf16 v[40:43], v[184:187], v[208:211], v[40:43]
	v_mfma_f32_16x16x32_bf16 v[24:27], v[180:183], v[212:215], v[24:27]
	v_mfma_f32_16x16x32_bf16 v[24:27], v[184:187], v[216:219], v[24:27]
	v_mfma_f32_16x16x32_bf16 v[20:23], v[188:191], v[212:215], v[20:23]
	v_mfma_f32_16x16x32_bf16 v[20:23], v[192:195], v[216:219], v[20:23]
	v_mfma_f32_16x16x32_bf16 v[4:7], v[188:191], v[228:231], v[4:7]
	v_mfma_f32_16x16x32_bf16 v[4:7], v[192:195], v[232:235], v[4:7]
	v_mfma_f32_16x16x32_bf16 v[8:11], v[180:183], v[228:231], v[8:11]
	v_mfma_f32_16x16x32_bf16 v[8:11], v[184:187], v[232:235], v[8:11]
	s_setprio 0
	s_barrier
	s_add_i32 s77, s77, 2
	s_add_u32 s71, s71, 0x2c0000
	s_addc_u32 s76, s76, 0
	s_add_u32 s50, s50, 0x100
	s_addc_u32 s51, s51, 0
	s_cmp_gt_u32 s77, 29
	s_cbranch_scc0 .Ltrail_1
.Lkdone_1:
	s_and_b64 vcc, exec, s[28:29]
	s_cbranch_vccz .LBB0_172
	s_barrier

.LBB0_242:
	s_ashr_i32 s57, s56, 31
	s_lshl_b64 s[36:37], s[56:57], 20
	s_add_u32 s58, s20, s36
	s_addc_u32 s59, s21, s37
	s_and_b64 s[36:37], s[42:43], exec
	s_cselect_b32 s36, s59, s45
	s_cselect_b32 s37, s58, s44
	s_ashr_i32 s55, s54, 31
	s_lshl_b64 s[46:47], s[54:55], 15
	s_add_u32 s60, s19, s46
	s_addc_u32 s61, s33, s47
	s_and_b64 s[46:47], s[42:43], exec
	s_cselect_b32 s55, s61, s35
	s_cselect_b32 s57, s60, s34
	s_add_u32 s63, s34, 0xe0000
	s_addc_u32 vcc_lo, s35, 0
	s_add_u32 s44, s44, 0x80080
	v_mov_b32_e32 v4, 0
	s_addc_u32 s45, s45, 0
	s_mov_b32 vcc_hi, -2
	v_mov_b32_e32 v5, v4
	v_mov_b32_e32 v6, v4
	v_mov_b32_e32 v7, v4
	v_mov_b32_e32 v8, v4
	v_mov_b32_e32 v9, v4
	v_mov_b32_e32 v10, v4
	v_mov_b32_e32 v11, v4
	v_mov_b32_e32 v20, v4
	v_mov_b32_e32 v21, v4
	v_mov_b32_e32 v22, v4
	v_mov_b32_e32 v23, v4
	v_mov_b32_e32 v24, v4
	v_mov_b32_e32 v25, v4
	v_mov_b32_e32 v26, v4
	v_mov_b32_e32 v27, v4
	v_mov_b32_e32 v36, v4
	v_mov_b32_e32 v37, v4
	s_waitcnt lgkmcnt(0)
	v_mov_b32_e32 v38, v4
	v_mov_b32_e32 v39, v4
	v_mov_b32_e32 v40, v4
	v_mov_b32_e32 v41, v4
	v_mov_b32_e32 v42, v4
	v_mov_b32_e32 v43, v4
	v_mov_b32_e32 v52, v4
	v_mov_b32_e32 v53, v4
	v_mov_b32_e32 v54, v4
	v_mov_b32_e32 v55, v4
	v_mov_b32_e32 v56, v4
	v_mov_b32_e32 v57, v4
	v_mov_b32_e32 v58, v4
	v_mov_b32_e32 v59, v4
	v_mov_b32_e32 v12, v4
	v_mov_b32_e32 v13, v4
	v_mov_b32_e32 v14, v4
	v_mov_b32_e32 v15, v4
	v_mov_b32_e32 v16, v4
	v_mov_b32_e32 v17, v4
	v_mov_b32_e32 v18, v4
	v_mov_b32_e32 v19, v4
	v_mov_b32_e32 v28, v4
	v_mov_b32_e32 v29, v4
	v_mov_b32_e32 v30, v4
	v_mov_b32_e32 v31, v4
	v_mov_b32_e32 v32, v4
	v_mov_b32_e32 v33, v4
	v_mov_b32_e32 v34, v4
	v_mov_b32_e32 v35, v4
	v_mov_b32_e32 v44, v4
	v_mov_b32_e32 v45, v4
	v_mov_b32_e32 v46, v4
	v_mov_b32_e32 v47, v4
	v_mov_b32_e32 v48, v4
	v_mov_b32_e32 v49, v4
	v_mov_b32_e32 v50, v4
	v_mov_b32_e32 v51, v4
	v_mov_b32_e32 v60, v4
	v_mov_b32_e32 v61, v4
	v_mov_b32_e32 v62, v4
	v_mov_b32_e32 v63, v4
	v_mov_b32_e32 v64, v4
	v_mov_b32_e32 v65, v4
	v_mov_b32_e32 v66, v4
	v_mov_b32_e32 v67, v4
	v_mov_b32_e32 v68, v4
	v_mov_b32_e32 v69, v4
	v_mov_b32_e32 v70, v4
	v_mov_b32_e32 v71, v4
	v_mov_b32_e32 v72, v4
	v_mov_b32_e32 v73, v4
	v_mov_b32_e32 v74, v4
	v_mov_b32_e32 v75, v4
	v_mov_b32_e32 v84, v4
	v_mov_b32_e32 v85, v4
	v_mov_b32_e32 v86, v4
	v_mov_b32_e32 v87, v4
	v_mov_b32_e32 v88, v4
	v_mov_b32_e32 v89, v4
	v_mov_b32_e32 v90, v4
	v_mov_b32_e32 v91, v4
	v_mov_b32_e32 v100, v4
	v_mov_b32_e32 v101, v4
	v_mov_b32_e32 v102, v4
	v_mov_b32_e32 v103, v4
	v_mov_b32_e32 v104, v4
	v_mov_b32_e32 v105, v4
	v_mov_b32_e32 v106, v4
	v_mov_b32_e32 v107, v4
	v_mov_b32_e32 v116, v4
	v_mov_b32_e32 v117, v4
	v_mov_b32_e32 v118, v4
	v_mov_b32_e32 v119, v4
	v_mov_b32_e32 v120, v4
	v_mov_b32_e32 v121, v4
	v_mov_b32_e32 v122, v4
	v_mov_b32_e32 v123, v4
	v_mov_b32_e32 v76, v4
	v_mov_b32_e32 v77, v4
	v_mov_b32_e32 v78, v4
	v_mov_b32_e32 v79, v4
	v_mov_b32_e32 v80, v4
	v_mov_b32_e32 v81, v4
	v_mov_b32_e32 v82, v4
	v_mov_b32_e32 v83, v4
	v_mov_b32_e32 v92, v4
	v_mov_b32_e32 v93, v4
	v_mov_b32_e32 v94, v4
	v_mov_b32_e32 v95, v4
	v_mov_b32_e32 v96, v4
	v_mov_b32_e32 v97, v4
	v_mov_b32_e32 v98, v4
	v_mov_b32_e32 v99, v4
	v_mov_b32_e32 v108, v4
	v_mov_b32_e32 v109, v4
	v_mov_b32_e32 v110, v4
	v_mov_b32_e32 v111, v4
	v_mov_b32_e32 v112, v4
	v_mov_b32_e32 v113, v4
	v_mov_b32_e32 v114, v4
	v_mov_b32_e32 v115, v4
	v_mov_b32_e32 v124, v4
	v_mov_b32_e32 v125, v4
	v_mov_b32_e32 v126, v4
	v_mov_b32_e32 v127, v4
	v_mov_b32_e32 v128, v4
	v_mov_b32_e32 v129, v4
	v_mov_b32_e32 v130, v4
	v_mov_b32_e32 v131, v4
	v_readfirstlane_b32 s101, v156
	s_bfe_u32 s101, s101, 0x10008
	s_cmp_lg_u32 s101, 0
	s_cbranch_scc1 .Ltrail_2
.LBB0_243:
	s_add_u32 s34, s44, 0xfff80080
	s_addc_u32 s35, s45, -1
	s_add_i32 s52, 0, 0x10000
	s_cmp_eq_u32 vcc_hi, 28
	s_cselect_b32 s47, s36, s35
	s_cselect_b32 s46, s37, s34
	s_cselect_b32 s35, s55, vcc_lo
	s_cselect_b32 s34, s57, s63
	s_add_i32 s68, 0, 0x14000
	v_add_u32_e32 v144, s52, v155
	v_add_u32_e32 v180, s68, v155
	ds_read_b128 v[132:135], v144
	ds_read_b128 v[136:139], v144 offset:1024
	ds_read_b128 v[140:143], v144 offset:2048
	ds_read_b128 v[144:147], v144 offset:3072
	ds_read_b128 v[176:179], v180
	ds_read_b128 v[182:185], v180 offset:1024
	ds_read_b128 v[186:189], v180 offset:2048
	ds_read_b128 v[190:193], v180 offset:3072
	v_lshl_add_u64 v[218:219], s[44:45], 0, v[172:173]
	s_add_i32 m0, s69, 0xc000
	ds_read_b128 v[194:197], v181
	ds_read_b128 v[198:201], v181 offset:1024
	ds_read_b128 v[202:205], v181 offset:2048
	ds_read_b128 v[206:209], v181 offset:3072
	ds_read_b128 v[210:213], v181 offset:4096
	ds_read_b128 v[214:217], v181 offset:5120
	ds_read_b128 v[228:231], v181 offset:6144
	ds_read_b128 v[232:235], v181 offset:7168
	global_load_lds_dwordx4 v[218:219], off
	v_lshl_add_u64 v[218:219], s[44:45], 0, v[174:175]
	s_add_i32 m0, s69, 0xe000
	s_nop 0
	global_load_lds_dwordx4 v[218:219], off
	s_waitcnt lgkmcnt(0)
	s_barrier
	s_setprio 1
	v_mfma_f32_16x16x32_bf16 v[128:131], v[132:135], v[194:197], v[128:131]
	v_mfma_f32_16x16x32_bf16 v[128:131], v[136:139], v[198:201], v[128:131]
	v_mfma_f32_16x16x32_bf16 v[124:127], v[140:143], v[194:197], v[124:127]
	v_mfma_f32_16x16x32_bf16 v[124:127], v[144:147], v[198:201], v[124:127]
	v_mfma_f32_16x16x32_bf16 v[108:111], v[140:143], v[202:205], v[108:111]
	v_mfma_f32_16x16x32_bf16 v[108:111], v[144:147], v[206:209], v[108:111]
	v_mfma_f32_16x16x32_bf16 v[112:115], v[132:135], v[202:205], v[112:115]
	v_mfma_f32_16x16x32_bf16 v[112:115], v[136:139], v[206:209], v[112:115]
	v_mfma_f32_16x16x32_bf16 v[96:99], v[132:135], v[210:213], v[96:99]
	v_mfma_f32_16x16x32_bf16 v[96:99], v[136:139], v[214:217], v[96:99]
	v_mfma_f32_16x16x32_bf16 v[92:95], v[140:143], v[210:213], v[92:95]
	v_mfma_f32_16x16x32_bf16 v[92:95], v[144:147], v[214:217], v[92:95]
	v_mfma_f32_16x16x32_bf16 v[76:79], v[140:143], v[228:231], v[76:79]
	v_mfma_f32_16x16x32_bf16 v[76:79], v[144:147], v[232:235], v[76:79]
	v_mfma_f32_16x16x32_bf16 v[80:83], v[132:135], v[228:231], v[80:83]
	v_mfma_f32_16x16x32_bf16 v[80:83], v[136:139], v[232:235], v[80:83]
	v_mfma_f32_16x16x32_bf16 v[120:123], v[176:179], v[194:197], v[120:123]
	v_mfma_f32_16x16x32_bf16 v[120:123], v[182:185], v[198:201], v[120:123]
	v_mfma_f32_16x16x32_bf16 v[116:119], v[186:189], v[194:197], v[116:119]
	v_mfma_f32_16x16x32_bf16 v[116:119], v[190:193], v[198:201], v[116:119]
	v_mfma_f32_16x16x32_bf16 v[100:103], v[186:189], v[202:205], v[100:103]
	v_mfma_f32_16x16x32_bf16 v[100:103], v[190:193], v[206:209], v[100:103]
	v_mfma_f32_16x16x32_bf16 v[104:107], v[176:179], v[202:205], v[104:107]
	v_mfma_f32_16x16x32_bf16 v[104:107], v[182:185], v[206:209], v[104:107]
	v_mfma_f32_16x16x32_bf16 v[88:91], v[176:179], v[210:213], v[88:91]
	v_mfma_f32_16x16x32_bf16 v[88:91], v[182:185], v[214:217], v[88:91]
	v_mfma_f32_16x16x32_bf16 v[84:87], v[186:189], v[210:213], v[84:87]
	v_mfma_f32_16x16x32_bf16 v[84:87], v[190:193], v[214:217], v[84:87]
	v_mfma_f32_16x16x32_bf16 v[68:71], v[186:189], v[228:231], v[68:71]
	v_mfma_f32_16x16x32_bf16 v[68:71], v[190:193], v[232:235], v[68:71]
	v_mfma_f32_16x16x32_bf16 v[72:75], v[176:179], v[228:231], v[72:75]
	v_mfma_f32_16x16x32_bf16 v[72:75], v[182:185], v[232:235], v[72:75]
	s_setprio 0
	s_waitcnt vmcnt(8)
	s_barrier
	s_add_i32 s52, s52, s2
	v_lshl_add_u64 v[218:219], s[34:35], 0, v[150:151]
	s_mov_b32 m0, s52
	ds_read_b128 v[194:197], v181 offset:16384
	ds_read_b128 v[198:201], v181 offset:17408
	ds_read_b128 v[202:205], v181 offset:18432
	ds_read_b128 v[206:209], v181 offset:19456
	ds_read_b128 v[210:213], v181 offset:20480
	ds_read_b128 v[214:217], v181 offset:21504
	ds_read_b128 v[228:231], v181 offset:22528
	ds_read_b128 v[232:235], v181 offset:23552
	global_load_lds_dwordx4 v[218:219], off
	s_add_i32 m0, s52, 0x2000
	s_add_u32 s52, s34, 0x4000
	v_lshl_add_u64 v[218:219], s[34:35], 0, v[0:1]
	s_addc_u32 s53, s35, 0
	s_add_i32 s68, s68, s2
	global_load_lds_dwordx4 v[218:219], off
	v_lshl_add_u64 v[218:219], s[52:53], 0, v[150:151]
	s_mov_b32 m0, s68
	v_lshl_add_u64 v[236:237], s[46:47], 0, v[148:149]
	global_load_lds_dwordx4 v[218:219], off
	v_lshl_add_u64 v[218:219], s[52:53], 0, v[0:1]
	s_add_i32 m0, s68, 0x2000
	s_nop 0
	global_load_lds_dwordx4 v[218:219], off
	v_lshl_add_u64 v[218:219], s[46:47], 0, v[152:153]
	s_mov_b32 m0, s69
	s_nop 0
	global_load_lds_dwordx4 v[218:219], off
	s_mov_b32 m0, s71
	s_nop 0
	global_load_lds_dwordx4 v[236:237], off
	s_waitcnt lgkmcnt(0)
	s_barrier
	s_setprio 1
	v_mfma_f32_16x16x32_bf16 v[64:67], v[132:135], v[194:197], v[64:67]
	v_mfma_f32_16x16x32_bf16 v[64:67], v[136:139], v[198:201], v[64:67]
	v_mfma_f32_16x16x32_bf16 v[60:63], v[140:143], v[194:197], v[60:63]
	v_mfma_f32_16x16x32_bf16 v[60:63], v[144:147], v[198:201], v[60:63]
	v_mfma_f32_16x16x32_bf16 v[44:47], v[140:143], v[202:205], v[44:47]
	v_mfma_f32_16x16x32_bf16 v[44:47], v[144:147], v[206:209], v[44:47]
	v_mfma_f32_16x16x32_bf16 v[48:51], v[132:135], v[202:205], v[48:51]
	v_mfma_f32_16x16x32_bf16 v[48:51], v[136:139], v[206:209], v[48:51]
	v_mfma_f32_16x16x32_bf16 v[32:35], v[132:135], v[210:213], v[32:35]
	v_mfma_f32_16x16x32_bf16 v[32:35], v[136:139], v[214:217], v[32:35]
	v_mfma_f32_16x16x32_bf16 v[28:31], v[140:143], v[210:213], v[28:31]
	v_mfma_f32_16x16x32_bf16 v[28:31], v[144:147], v[214:217], v[28:31]
	v_mfma_f32_16x16x32_bf16 v[12:15], v[140:143], v[228:231], v[12:15]
	v_mfma_f32_16x16x32_bf16 v[12:15], v[144:147], v[232:235], v[12:15]
	v_mfma_f32_16x16x32_bf16 v[16:19], v[132:135], v[228:231], v[16:19]
	v_mfma_f32_16x16x32_bf16 v[16:19], v[136:139], v[232:235], v[16:19]
	v_mfma_f32_16x16x32_bf16 v[56:59], v[176:179], v[194:197], v[56:59]
	v_mfma_f32_16x16x32_bf16 v[56:59], v[182:185], v[198:201], v[56:59]
	v_mfma_f32_16x16x32_bf16 v[52:55], v[186:189], v[194:197], v[52:55]
	v_mfma_f32_16x16x32_bf16 v[52:55], v[190:193], v[198:201], v[52:55]
	v_mfma_f32_16x16x32_bf16 v[36:39], v[186:189], v[202:205], v[36:39]
	v_mfma_f32_16x16x32_bf16 v[36:39], v[190:193], v[206:209], v[36:39]
	v_mfma_f32_16x16x32_bf16 v[40:43], v[176:179], v[202:205], v[40:43]
	v_mfma_f32_16x16x32_bf16 v[40:43], v[182:185], v[206:209], v[40:43]
	v_mfma_f32_16x16x32_bf16 v[24:27], v[176:179], v[210:213], v[24:27]
	v_mfma_f32_16x16x32_bf16 v[24:27], v[182:185], v[214:217], v[24:27]
	v_mfma_f32_16x16x32_bf16 v[20:23], v[186:189], v[210:213], v[20:23]
	v_mfma_f32_16x16x32_bf16 v[20:23], v[190:193], v[214:217], v[20:23]
	v_mfma_f32_16x16x32_bf16 v[4:7], v[186:189], v[228:231], v[4:7]
	v_mfma_f32_16x16x32_bf16 v[4:7], v[190:193], v[232:235], v[4:7]
	v_mfma_f32_16x16x32_bf16 v[8:11], v[176:179], v[228:231], v[8:11]
	v_mfma_f32_16x16x32_bf16 v[8:11], v[182:185], v[232:235], v[8:11]
	s_setprio 0
	s_waitcnt vmcnt(8)
	s_barrier
	s_add_i32 s52, 0, 0x18000
	s_add_i32 s53, 0, 0x1c000
	v_add_u32_e32 v144, s52, v155
	v_add_u32_e32 v180, s53, v155
	ds_read_b128 v[132:135], v144
	ds_read_b128 v[136:139], v144 offset:1024
	ds_read_b128 v[140:143], v144 offset:2048
	ds_read_b128 v[144:147], v144 offset:3072
	ds_read_b128 v[176:179], v180
	ds_read_b128 v[182:185], v180 offset:1024
	ds_read_b128 v[186:189], v180 offset:2048
	ds_read_b128 v[190:193], v180 offset:3072
	s_add_u32 s46, s46, 0x80000
	s_addc_u32 s47, s47, 0
	s_mov_b32 m0, s88
	v_lshl_add_u64 v[238:239], s[46:47], 0, v[152:153]
	ds_read_b128 v[194:197], v181 offset:32768
	ds_read_b128 v[198:201], v181 offset:33792
	ds_read_b128 v[202:205], v181 offset:34816
	ds_read_b128 v[206:209], v181 offset:35840
	ds_read_b128 v[210:213], v181 offset:36864
	ds_read_b128 v[214:217], v181 offset:37888
	ds_read_b128 v[228:231], v181 offset:38912
	ds_read_b128 v[232:235], v181 offset:39936
	global_load_lds_dwordx4 v[238:239], off
	v_lshl_add_u64 v[238:239], s[46:47], 0, v[148:149]
	s_mov_b32 m0, s96
	s_nop 0
	global_load_lds_dwordx4 v[238:239], off
	s_waitcnt lgkmcnt(0)
	s_barrier
	s_setprio 1
	v_mfma_f32_16x16x32_bf16 v[128:131], v[132:135], v[194:197], v[128:131]
	v_mfma_f32_16x16x32_bf16 v[128:131], v[136:139], v[198:201], v[128:131]
	v_mfma_f32_16x16x32_bf16 v[124:127], v[140:143], v[194:197], v[124:127]
	v_mfma_f32_16x16x32_bf16 v[124:127], v[144:147], v[198:201], v[124:127]
	v_mfma_f32_16x16x32_bf16 v[108:111], v[140:143], v[202:205], v[108:111]
	v_mfma_f32_16x16x32_bf16 v[108:111], v[144:147], v[206:209], v[108:111]
	v_mfma_f32_16x16x32_bf16 v[112:115], v[132:135], v[202:205], v[112:115]
	v_mfma_f32_16x16x32_bf16 v[112:115], v[136:139], v[206:209], v[112:115]
	v_mfma_f32_16x16x32_bf16 v[96:99], v[132:135], v[210:213], v[96:99]
	v_mfma_f32_16x16x32_bf16 v[96:99], v[136:139], v[214:217], v[96:99]
	v_mfma_f32_16x16x32_bf16 v[92:95], v[140:143], v[210:213], v[92:95]
	v_mfma_f32_16x16x32_bf16 v[92:95], v[144:147], v[214:217], v[92:95]
	v_mfma_f32_16x16x32_bf16 v[76:79], v[140:143], v[228:231], v[76:79]
	v_mfma_f32_16x16x32_bf16 v[76:79], v[144:147], v[232:235], v[76:79]
	v_mfma_f32_16x16x32_bf16 v[80:83], v[132:135], v[228:231], v[80:83]
	v_mfma_f32_16x16x32_bf16 v[80:83], v[136:139], v[232:235], v[80:83]
	v_mfma_f32_16x16x32_bf16 v[120:123], v[176:179], v[194:197], v[120:123]
	v_mfma_f32_16x16x32_bf16 v[120:123], v[182:185], v[198:201], v[120:123]
	v_mfma_f32_16x16x32_bf16 v[116:119], v[186:189], v[194:197], v[116:119]
	v_mfma_f32_16x16x32_bf16 v[116:119], v[190:193], v[198:201], v[116:119]
	v_mfma_f32_16x16x32_bf16 v[100:103], v[186:189], v[202:205], v[100:103]
	v_mfma_f32_16x16x32_bf16 v[100:103], v[190:193], v[206:209], v[100:103]
	v_mfma_f32_16x16x32_bf16 v[104:107], v[176:179], v[202:205], v[104:107]
	v_mfma_f32_16x16x32_bf16 v[104:107], v[182:185], v[206:209], v[104:107]
	v_mfma_f32_16x16x32_bf16 v[88:91], v[176:179], v[210:213], v[88:91]
	v_mfma_f32_16x16x32_bf16 v[88:91], v[182:185], v[214:217], v[88:91]
	v_mfma_f32_16x16x32_bf16 v[84:87], v[186:189], v[210:213], v[84:87]
	v_mfma_f32_16x16x32_bf16 v[84:87], v[190:193], v[214:217], v[84:87]
	v_mfma_f32_16x16x32_bf16 v[68:71], v[186:189], v[228:231], v[68:71]
	v_mfma_f32_16x16x32_bf16 v[68:71], v[190:193], v[232:235], v[68:71]
	v_mfma_f32_16x16x32_bf16 v[72:75], v[176:179], v[228:231], v[72:75]
	v_mfma_f32_16x16x32_bf16 v[72:75], v[182:185], v[232:235], v[72:75]
	s_setprio 0
	s_waitcnt vmcnt(8)
	s_barrier
	s_add_u32 s46, s34, 0x70000
	s_addc_u32 s47, s35, 0
	s_add_i32 s52, s52, s2
	v_lshl_add_u64 v[238:239], s[46:47], 0, v[150:151]
	s_mov_b32 m0, s52
	ds_read_b128 v[194:197], v181 offset:49152
	ds_read_b128 v[198:201], v181 offset:50176
	ds_read_b128 v[202:205], v181 offset:51200
	ds_read_b128 v[206:209], v181 offset:52224
	ds_read_b128 v[210:213], v181 offset:53248
	ds_read_b128 v[214:217], v181 offset:54272
	ds_read_b128 v[228:231], v181 offset:55296
	ds_read_b128 v[232:235], v181 offset:56320
	global_load_lds_dwordx4 v[238:239], off
	s_add_i32 m0, s52, 0x2000
	s_add_u32 s34, s34, 0x74000
	v_lshl_add_u64 v[238:239], s[46:47], 0, v[0:1]
	s_addc_u32 s35, s35, 0
	s_add_i32 s46, s53, s2
	global_load_lds_dwordx4 v[238:239], off
	v_lshl_add_u64 v[238:239], s[34:35], 0, v[150:151]
	s_mov_b32 m0, s46
	v_lshl_add_u64 v[218:219], v[218:219], 0, s[14:15]
	global_load_lds_dwordx4 v[238:239], off
	v_lshl_add_u64 v[238:239], s[34:35], 0, v[0:1]
	s_add_i32 m0, s46, 0x2000
	s_nop 0
	global_load_lds_dwordx4 v[238:239], off
	s_mov_b32 m0, s97
	s_nop 0
	global_load_lds_dwordx4 v[218:219], off
	v_lshl_add_u64 v[218:219], v[236:237], 0, s[14:15]
	s_mov_b32 m0, s76
	s_nop 0
	global_load_lds_dwordx4 v[218:219], off
	s_waitcnt lgkmcnt(0)
	s_barrier
	s_setprio 1
	v_mfma_f32_16x16x32_bf16 v[64:67], v[132:135], v[194:197], v[64:67]
	v_mfma_f32_16x16x32_bf16 v[64:67], v[136:139], v[198:201], v[64:67]
	v_mfma_f32_16x16x32_bf16 v[60:63], v[140:143], v[194:197], v[60:63]
	v_mfma_f32_16x16x32_bf16 v[60:63], v[144:147], v[198:201], v[60:63]
	v_mfma_f32_16x16x32_bf16 v[44:47], v[140:143], v[202:205], v[44:47]
	v_mfma_f32_16x16x32_bf16 v[44:47], v[144:147], v[206:209], v[44:47]
	v_mfma_f32_16x16x32_bf16 v[48:51], v[132:135], v[202:205], v[48:51]
	v_mfma_f32_16x16x32_bf16 v[48:51], v[136:139], v[206:209], v[48:51]
	v_mfma_f32_16x16x32_bf16 v[32:35], v[132:135], v[210:213], v[32:35]
	v_mfma_f32_16x16x32_bf16 v[32:35], v[136:139], v[214:217], v[32:35]
	v_mfma_f32_16x16x32_bf16 v[28:31], v[140:143], v[210:213], v[28:31]
	v_mfma_f32_16x16x32_bf16 v[28:31], v[144:147], v[214:217], v[28:31]
	v_mfma_f32_16x16x32_bf16 v[12:15], v[140:143], v[228:231], v[12:15]
	v_mfma_f32_16x16x32_bf16 v[12:15], v[144:147], v[232:235], v[12:15]
	v_mfma_f32_16x16x32_bf16 v[16:19], v[132:135], v[228:231], v[16:19]
	v_mfma_f32_16x16x32_bf16 v[16:19], v[136:139], v[232:235], v[16:19]
	v_mfma_f32_16x16x32_bf16 v[56:59], v[176:179], v[194:197], v[56:59]
	v_mfma_f32_16x16x32_bf16 v[56:59], v[182:185], v[198:201], v[56:59]
	v_mfma_f32_16x16x32_bf16 v[52:55], v[186:189], v[194:197], v[52:55]
	v_mfma_f32_16x16x32_bf16 v[52:55], v[190:193], v[198:201], v[52:55]
	v_mfma_f32_16x16x32_bf16 v[36:39], v[186:189], v[202:205], v[36:39]
	v_mfma_f32_16x16x32_bf16 v[36:39], v[190:193], v[206:209], v[36:39]
	v_mfma_f32_16x16x32_bf16 v[40:43], v[176:179], v[202:205], v[40:43]
	v_mfma_f32_16x16x32_bf16 v[40:43], v[182:185], v[206:209], v[40:43]
	v_mfma_f32_16x16x32_bf16 v[24:27], v[176:179], v[210:213], v[24:27]
	v_mfma_f32_16x16x32_bf16 v[24:27], v[182:185], v[214:217], v[24:27]
	v_mfma_f32_16x16x32_bf16 v[20:23], v[186:189], v[210:213], v[20:23]
	v_mfma_f32_16x16x32_bf16 v[20:23], v[190:193], v[214:217], v[20:23]
	v_mfma_f32_16x16x32_bf16 v[4:7], v[186:189], v[228:231], v[4:7]
	v_mfma_f32_16x16x32_bf16 v[4:7], v[190:193], v[232:235], v[4:7]
	v_mfma_f32_16x16x32_bf16 v[8:11], v[176:179], v[228:231], v[8:11]
	v_mfma_f32_16x16x32_bf16 v[8:11], v[182:185], v[232:235], v[8:11]
	s_setprio 0
	s_waitcnt vmcnt(8)
	s_barrier
	s_add_i32 vcc_hi, vcc_hi, 2
	s_add_u32 s63, s63, 0xe0000
	s_addc_u32 vcc_lo, vcc_lo, 0
	s_add_u32 s44, s44, 0x100
	s_addc_u32 s45, s45, 0
	s_cmp_gt_u32 vcc_hi, 29
	s_cbranch_scc0 .LBB0_243
	s_branch .Lkdone_2
.Ltrail_2:
	s_add_u32 s34, s44, 0xfff80080
	s_addc_u32 s35, s45, -1
	s_add_i32 s52, 0, 0x10000
	s_cmp_eq_u32 vcc_hi, 28
	s_cselect_b32 s47, s36, s35
	s_cselect_b32 s46, s37, s34
	s_cselect_b32 s35, s55, vcc_lo
	s_cselect_b32 s34, s57, s63
	s_add_i32 s68, 0, 0x14000
	v_add_u32_e32 v144, s52, v155
	v_add_u32_e32 v180, s68, v155
	ds_read_b128 v[132:135], v144
	ds_read_b128 v[136:139], v144 offset:1024
	ds_read_b128 v[140:143], v144 offset:2048
	ds_read_b128 v[144:147], v144 offset:3072
	ds_read_b128 v[176:179], v180
	ds_read_b128 v[182:185], v180 offset:1024
	ds_read_b128 v[186:189], v180 offset:2048
	ds_read_b128 v[190:193], v180 offset:3072
	v_lshl_add_u64 v[218:219], s[44:45], 0, v[172:173]
	s_add_i32 m0, s69, 0xc000
	ds_read_b128 v[194:197], v181
	ds_read_b128 v[198:201], v181 offset:1024
	ds_read_b128 v[202:205], v181 offset:2048
	ds_read_b128 v[206:209], v181 offset:3072
	ds_read_b128 v[210:213], v181 offset:4096
	ds_read_b128 v[214:217], v181 offset:5120
	ds_read_b128 v[228:231], v181 offset:6144
	ds_read_b128 v[232:235], v181 offset:7168
	global_load_lds_dwordx4 v[218:219], off
	v_lshl_add_u64 v[218:219], s[44:45], 0, v[174:175]
	s_add_i32 m0, s69, 0xe000
	s_nop 0
	global_load_lds_dwordx4 v[218:219], off
	s_waitcnt vmcnt(8)
	s_waitcnt lgkmcnt(0)
	s_barrier
	s_setprio 1
	v_mfma_f32_16x16x32_bf16 v[128:131], v[132:135], v[194:197], v[128:131]
	v_mfma_f32_16x16x32_bf16 v[128:131], v[136:139], v[198:201], v[128:131]
	v_mfma_f32_16x16x32_bf16 v[124:127], v[140:143], v[194:197], v[124:127]
	v_mfma_f32_16x16x32_bf16 v[124:127], v[144:147], v[198:201], v[124:127]
	v_mfma_f32_16x16x32_bf16 v[108:111], v[140:143], v[202:205], v[108:111]
	v_mfma_f32_16x16x32_bf16 v[108:111], v[144:147], v[206:209], v[108:111]
	v_mfma_f32_16x16x32_bf16 v[112:115], v[132:135], v[202:205], v[112:115]
	v_mfma_f32_16x16x32_bf16 v[112:115], v[136:139], v[206:209], v[112:115]
	v_mfma_f32_16x16x32_bf16 v[96:99], v[132:135], v[210:213], v[96:99]
	v_mfma_f32_16x16x32_bf16 v[96:99], v[136:139], v[214:217], v[96:99]
	v_mfma_f32_16x16x32_bf16 v[92:95], v[140:143], v[210:213], v[92:95]
	v_mfma_f32_16x16x32_bf16 v[92:95], v[144:147], v[214:217], v[92:95]
	v_mfma_f32_16x16x32_bf16 v[76:79], v[140:143], v[228:231], v[76:79]
	v_mfma_f32_16x16x32_bf16 v[76:79], v[144:147], v[232:235], v[76:79]
	v_mfma_f32_16x16x32_bf16 v[80:83], v[132:135], v[228:231], v[80:83]
	v_mfma_f32_16x16x32_bf16 v[80:83], v[136:139], v[232:235], v[80:83]
	v_mfma_f32_16x16x32_bf16 v[120:123], v[176:179], v[194:197], v[120:123]
	v_mfma_f32_16x16x32_bf16 v[120:123], v[182:185], v[198:201], v[120:123]
	v_mfma_f32_16x16x32_bf16 v[116:119], v[186:189], v[194:197], v[116:119]
	v_mfma_f32_16x16x32_bf16 v[116:119], v[190:193], v[198:201], v[116:119]
	v_mfma_f32_16x16x32_bf16 v[100:103], v[186:189], v[202:205], v[100:103]
	v_mfma_f32_16x16x32_bf16 v[100:103], v[190:193], v[206:209], v[100:103]
	v_mfma_f32_16x16x32_bf16 v[104:107], v[176:179], v[202:205], v[104:107]
	v_mfma_f32_16x16x32_bf16 v[104:107], v[182:185], v[206:209], v[104:107]
	v_mfma_f32_16x16x32_bf16 v[88:91], v[176:179], v[210:213], v[88:91]
	v_mfma_f32_16x16x32_bf16 v[88:91], v[182:185], v[214:217], v[88:91]
	v_mfma_f32_16x16x32_bf16 v[84:87], v[186:189], v[210:213], v[84:87]
	v_mfma_f32_16x16x32_bf16 v[84:87], v[190:193], v[214:217], v[84:87]
	v_mfma_f32_16x16x32_bf16 v[68:71], v[186:189], v[228:231], v[68:71]
	v_mfma_f32_16x16x32_bf16 v[68:71], v[190:193], v[232:235], v[68:71]
	v_mfma_f32_16x16x32_bf16 v[72:75], v[176:179], v[228:231], v[72:75]
	v_mfma_f32_16x16x32_bf16 v[72:75], v[182:185], v[232:235], v[72:75]
	s_setprio 0
	s_barrier
	s_add_i32 s52, s52, s2
	v_lshl_add_u64 v[218:219], s[34:35], 0, v[150:151]
	s_mov_b32 m0, s52
	ds_read_b128 v[194:197], v181 offset:16384
	ds_read_b128 v[198:201], v181 offset:17408
	ds_read_b128 v[202:205], v181 offset:18432
	ds_read_b128 v[206:209], v181 offset:19456
	ds_read_b128 v[210:213], v181 offset:20480
	ds_read_b128 v[214:217], v181 offset:21504
	ds_read_b128 v[228:231], v181 offset:22528
	ds_read_b128 v[232:235], v181 offset:23552
	global_load_lds_dwordx4 v[218:219], off
	s_add_i32 m0, s52, 0x2000
	s_add_u32 s52, s34, 0x4000
	v_lshl_add_u64 v[218:219], s[34:35], 0, v[0:1]
	s_addc_u32 s53, s35, 0
	s_add_i32 s68, s68, s2
	global_load_lds_dwordx4 v[218:219], off
	v_lshl_add_u64 v[218:219], s[52:53], 0, v[150:151]
	s_mov_b32 m0, s68
	v_lshl_add_u64 v[236:237], s[46:47], 0, v[148:149]
	global_load_lds_dwordx4 v[218:219], off
	v_lshl_add_u64 v[218:219], s[52:53], 0, v[0:1]
	s_add_i32 m0, s68, 0x2000
	s_nop 0
	global_load_lds_dwordx4 v[218:219], off
	v_lshl_add_u64 v[218:219], s[46:47], 0, v[152:153]
	s_mov_b32 m0, s69
	s_nop 0
	global_load_lds_dwordx4 v[218:219], off
	s_mov_b32 m0, s71
	s_nop 0
	global_load_lds_dwordx4 v[236:237], off
	s_waitcnt vmcnt(8)
	s_waitcnt lgkmcnt(0)
	s_barrier
	s_setprio 1
	v_mfma_f32_16x16x32_bf16 v[64:67], v[132:135], v[194:197], v[64:67]
	v_mfma_f32_16x16x32_bf16 v[64:67], v[136:139], v[198:201], v[64:67]
	v_mfma_f32_16x16x32_bf16 v[60:63], v[140:143], v[194:197], v[60:63]
	v_mfma_f32_16x16x32_bf16 v[60:63], v[144:147], v[198:201], v[60:63]
	v_mfma_f32_16x16x32_bf16 v[44:47], v[140:143], v[202:205], v[44:47]
	v_mfma_f32_16x16x32_bf16 v[44:47], v[144:147], v[206:209], v[44:47]
	v_mfma_f32_16x16x32_bf16 v[48:51], v[132:135], v[202:205], v[48:51]
	v_mfma_f32_16x16x32_bf16 v[48:51], v[136:139], v[206:209], v[48:51]
	v_mfma_f32_16x16x32_bf16 v[32:35], v[132:135], v[210:213], v[32:35]
	v_mfma_f32_16x16x32_bf16 v[32:35], v[136:139], v[214:217], v[32:35]
	v_mfma_f32_16x16x32_bf16 v[28:31], v[140:143], v[210:213], v[28:31]
	v_mfma_f32_16x16x32_bf16 v[28:31], v[144:147], v[214:217], v[28:31]
	v_mfma_f32_16x16x32_bf16 v[12:15], v[140:143], v[228:231], v[12:15]
	v_mfma_f32_16x16x32_bf16 v[12:15], v[144:147], v[232:235], v[12:15]
	v_mfma_f32_16x16x32_bf16 v[16:19], v[132:135], v[228:231], v[16:19]
	v_mfma_f32_16x16x32_bf16 v[16:19], v[136:139], v[232:235], v[16:19]
	v_mfma_f32_16x16x32_bf16 v[56:59], v[176:179], v[194:197], v[56:59]
	v_mfma_f32_16x16x32_bf16 v[56:59], v[182:185], v[198:201], v[56:59]
	v_mfma_f32_16x16x32_bf16 v[52:55], v[186:189], v[194:197], v[52:55]
	v_mfma_f32_16x16x32_bf16 v[52:55], v[190:193], v[198:201], v[52:55]
	v_mfma_f32_16x16x32_bf16 v[36:39], v[186:189], v[202:205], v[36:39]
	v_mfma_f32_16x16x32_bf16 v[36:39], v[190:193], v[206:209], v[36:39]
	v_mfma_f32_16x16x32_bf16 v[40:43], v[176:179], v[202:205], v[40:43]
	v_mfma_f32_16x16x32_bf16 v[40:43], v[182:185], v[206:209], v[40:43]
	v_mfma_f32_16x16x32_bf16 v[24:27], v[176:179], v[210:213], v[24:27]
	v_mfma_f32_16x16x32_bf16 v[24:27], v[182:185], v[214:217], v[24:27]
	v_mfma_f32_16x16x32_bf16 v[20:23], v[186:189], v[210:213], v[20:23]
	v_mfma_f32_16x16x32_bf16 v[20:23], v[190:193], v[214:217], v[20:23]
	v_mfma_f32_16x16x32_bf16 v[4:7], v[186:189], v[228:231], v[4:7]
	v_mfma_f32_16x16x32_bf16 v[4:7], v[190:193], v[232:235], v[4:7]
	v_mfma_f32_16x16x32_bf16 v[8:11], v[176:179], v[228:231], v[8:11]
	v_mfma_f32_16x16x32_bf16 v[8:11], v[182:185], v[232:235], v[8:11]
	s_setprio 0
	s_barrier
	s_add_i32 s52, 0, 0x18000
	s_add_i32 s53, 0, 0x1c000
	v_add_u32_e32 v144, s52, v155
	v_add_u32_e32 v180, s53, v155
	ds_read_b128 v[132:135], v144
	ds_read_b128 v[136:139], v144 offset:1024
	ds_read_b128 v[140:143], v144 offset:2048
	ds_read_b128 v[144:147], v144 offset:3072
	ds_read_b128 v[176:179], v180
	ds_read_b128 v[182:185], v180 offset:1024
	ds_read_b128 v[186:189], v180 offset:2048
	ds_read_b128 v[190:193], v180 offset:3072
	s_add_u32 s46, s46, 0x80000
	s_addc_u32 s47, s47, 0
	s_mov_b32 m0, s88
	v_lshl_add_u64 v[238:239], s[46:47], 0, v[152:153]
	ds_read_b128 v[194:197], v181 offset:32768
	ds_read_b128 v[198:201], v181 offset:33792
	ds_read_b128 v[202:205], v181 offset:34816
	ds_read_b128 v[206:209], v181 offset:35840
	ds_read_b128 v[210:213], v181 offset:36864
	ds_read_b128 v[214:217], v181 offset:37888
	ds_read_b128 v[228:231], v181 offset:38912
	ds_read_b128 v[232:235], v181 offset:39936
	global_load_lds_dwordx4 v[238:239], off
	v_lshl_add_u64 v[238:239], s[46:47], 0, v[148:149]
	s_mov_b32 m0, s96
	s_nop 0
	global_load_lds_dwordx4 v[238:239], off
	s_waitcnt vmcnt(8)
	s_waitcnt lgkmcnt(0)
	s_barrier
	s_setprio 1
	v_mfma_f32_16x16x32_bf16 v[128:131], v[132:135], v[194:197], v[128:131]
	v_mfma_f32_16x16x32_bf16 v[128:131], v[136:139], v[198:201], v[128:131]
	v_mfma_f32_16x16x32_bf16 v[124:127], v[140:143], v[194:197], v[124:127]
	v_mfma_f32_16x16x32_bf16 v[124:127], v[144:147], v[198:201], v[124:127]
	v_mfma_f32_16x16x32_bf16 v[108:111], v[140:143], v[202:205], v[108:111]
	v_mfma_f32_16x16x32_bf16 v[108:111], v[144:147], v[206:209], v[108:111]
	v_mfma_f32_16x16x32_bf16 v[112:115], v[132:135], v[202:205], v[112:115]
	v_mfma_f32_16x16x32_bf16 v[112:115], v[136:139], v[206:209], v[112:115]
	v_mfma_f32_16x16x32_bf16 v[96:99], v[132:135], v[210:213], v[96:99]
	v_mfma_f32_16x16x32_bf16 v[96:99], v[136:139], v[214:217], v[96:99]
	v_mfma_f32_16x16x32_bf16 v[92:95], v[140:143], v[210:213], v[92:95]
	v_mfma_f32_16x16x32_bf16 v[92:95], v[144:147], v[214:217], v[92:95]
	v_mfma_f32_16x16x32_bf16 v[76:79], v[140:143], v[228:231], v[76:79]
	v_mfma_f32_16x16x32_bf16 v[76:79], v[144:147], v[232:235], v[76:79]
	v_mfma_f32_16x16x32_bf16 v[80:83], v[132:135], v[228:231], v[80:83]
	v_mfma_f32_16x16x32_bf16 v[80:83], v[136:139], v[232:235], v[80:83]
	v_mfma_f32_16x16x32_bf16 v[120:123], v[176:179], v[194:197], v[120:123]
	v_mfma_f32_16x16x32_bf16 v[120:123], v[182:185], v[198:201], v[120:123]
	v_mfma_f32_16x16x32_bf16 v[116:119], v[186:189], v[194:197], v[116:119]
	v_mfma_f32_16x16x32_bf16 v[116:119], v[190:193], v[198:201], v[116:119]
	v_mfma_f32_16x16x32_bf16 v[100:103], v[186:189], v[202:205], v[100:103]
	v_mfma_f32_16x16x32_bf16 v[100:103], v[190:193], v[206:209], v[100:103]
	v_mfma_f32_16x16x32_bf16 v[104:107], v[176:179], v[202:205], v[104:107]
	v_mfma_f32_16x16x32_bf16 v[104:107], v[182:185], v[206:209], v[104:107]
	v_mfma_f32_16x16x32_bf16 v[88:91], v[176:179], v[210:213], v[88:91]
	v_mfma_f32_16x16x32_bf16 v[88:91], v[182:185], v[214:217], v[88:91]
	v_mfma_f32_16x16x32_bf16 v[84:87], v[186:189], v[210:213], v[84:87]
	v_mfma_f32_16x16x32_bf16 v[84:87], v[190:193], v[214:217], v[84:87]
	v_mfma_f32_16x16x32_bf16 v[68:71], v[186:189], v[228:231], v[68:71]
	v_mfma_f32_16x16x32_bf16 v[68:71], v[190:193], v[232:235], v[68:71]
	v_mfma_f32_16x16x32_bf16 v[72:75], v[176:179], v[228:231], v[72:75]
	v_mfma_f32_16x16x32_bf16 v[72:75], v[182:185], v[232:235], v[72:75]
	s_setprio 0
	s_barrier
	s_add_u32 s46, s34, 0x70000
	s_addc_u32 s47, s35, 0
	s_add_i32 s52, s52, s2
	v_lshl_add_u64 v[238:239], s[46:47], 0, v[150:151]
	s_mov_b32 m0, s52
	ds_read_b128 v[194:197], v181 offset:49152
	ds_read_b128 v[198:201], v181 offset:50176
	ds_read_b128 v[202:205], v181 offset:51200
	ds_read_b128 v[206:209], v181 offset:52224
	ds_read_b128 v[210:213], v181 offset:53248
	ds_read_b128 v[214:217], v181 offset:54272
	ds_read_b128 v[228:231], v181 offset:55296
	ds_read_b128 v[232:235], v181 offset:56320
	global_load_lds_dwordx4 v[238:239], off
	s_add_i32 m0, s52, 0x2000
	s_add_u32 s34, s34, 0x74000
	v_lshl_add_u64 v[238:239], s[46:47], 0, v[0:1]
	s_addc_u32 s35, s35, 0
	s_add_i32 s46, s53, s2
	global_load_lds_dwordx4 v[238:239], off
	v_lshl_add_u64 v[238:239], s[34:35], 0, v[150:151]
	s_mov_b32 m0, s46
	v_lshl_add_u64 v[218:219], v[218:219], 0, s[14:15]
	global_load_lds_dwordx4 v[238:239], off
	v_lshl_add_u64 v[238:239], s[34:35], 0, v[0:1]
	s_add_i32 m0, s46, 0x2000
	s_nop 0
	global_load_lds_dwordx4 v[238:239], off
	s_mov_b32 m0, s97
	s_nop 0
	global_load_lds_dwordx4 v[218:219], off
	v_lshl_add_u64 v[218:219], v[236:237], 0, s[14:15]
	s_mov_b32 m0, s76
	s_nop 0
	global_load_lds_dwordx4 v[218:219], off
	s_waitcnt vmcnt(8)
	s_waitcnt lgkmcnt(0)
	s_barrier
	s_setprio 1
	v_mfma_f32_16x16x32_bf16 v[64:67], v[132:135], v[194:197], v[64:67]
	v_mfma_f32_16x16x32_bf16 v[64:67], v[136:139], v[198:201], v[64:67]
	v_mfma_f32_16x16x32_bf16 v[60:63], v[140:143], v[194:197], v[60:63]
	v_mfma_f32_16x16x32_bf16 v[60:63], v[144:147], v[198:201], v[60:63]
	v_mfma_f32_16x16x32_bf16 v[44:47], v[140:143], v[202:205], v[44:47]
	v_mfma_f32_16x16x32_bf16 v[44:47], v[144:147], v[206:209], v[44:47]
	v_mfma_f32_16x16x32_bf16 v[48:51], v[132:135], v[202:205], v[48:51]
	v_mfma_f32_16x16x32_bf16 v[48:51], v[136:139], v[206:209], v[48:51]
	v_mfma_f32_16x16x32_bf16 v[32:35], v[132:135], v[210:213], v[32:35]
	v_mfma_f32_16x16x32_bf16 v[32:35], v[136:139], v[214:217], v[32:35]
	v_mfma_f32_16x16x32_bf16 v[28:31], v[140:143], v[210:213], v[28:31]
	v_mfma_f32_16x16x32_bf16 v[28:31], v[144:147], v[214:217], v[28:31]
	v_mfma_f32_16x16x32_bf16 v[12:15], v[140:143], v[228:231], v[12:15]
	v_mfma_f32_16x16x32_bf16 v[12:15], v[144:147], v[232:235], v[12:15]
	v_mfma_f32_16x16x32_bf16 v[16:19], v[132:135], v[228:231], v[16:19]
	v_mfma_f32_16x16x32_bf16 v[16:19], v[136:139], v[232:235], v[16:19]
	v_mfma_f32_16x16x32_bf16 v[56:59], v[176:179], v[194:197], v[56:59]
	v_mfma_f32_16x16x32_bf16 v[56:59], v[182:185], v[198:201], v[56:59]
	v_mfma_f32_16x16x32_bf16 v[52:55], v[186:189], v[194:197], v[52:55]
	v_mfma_f32_16x16x32_bf16 v[52:55], v[190:193], v[198:201], v[52:55]
	v_mfma_f32_16x16x32_bf16 v[36:39], v[186:189], v[202:205], v[36:39]
	v_mfma_f32_16x16x32_bf16 v[36:39], v[190:193], v[206:209], v[36:39]
	v_mfma_f32_16x16x32_bf16 v[40:43], v[176:179], v[202:205], v[40:43]
	v_mfma_f32_16x16x32_bf16 v[40:43], v[182:185], v[206:209], v[40:43]
	v_mfma_f32_16x16x32_bf16 v[24:27], v[176:179], v[210:213], v[24:27]
	v_mfma_f32_16x16x32_bf16 v[24:27], v[182:185], v[214:217], v[24:27]
	v_mfma_f32_16x16x32_bf16 v[20:23], v[186:189], v[210:213], v[20:23]
	v_mfma_f32_16x16x32_bf16 v[20:23], v[190:193], v[214:217], v[20:23]
	v_mfma_f32_16x16x32_bf16 v[4:7], v[186:189], v[228:231], v[4:7]
	v_mfma_f32_16x16x32_bf16 v[4:7], v[190:193], v[232:235], v[4:7]
	v_mfma_f32_16x16x32_bf16 v[8:11], v[176:179], v[228:231], v[8:11]
	v_mfma_f32_16x16x32_bf16 v[8:11], v[182:185], v[232:235], v[8:11]
	s_setprio 0
	s_barrier
	s_add_i32 vcc_hi, vcc_hi, 2
	s_add_u32 s63, s63, 0xe0000
	s_addc_u32 vcc_lo, vcc_lo, 0
	s_add_u32 s44, s44, 0x100
	s_addc_u32 s45, s45, 0
	s_cmp_gt_u32 vcc_hi, 29
	s_cbranch_scc0 .Ltrail_2

.LBB0_558:
	s_ashr_i32 s49, s48, 31
	s_lshl_b64 s[36:37], s[48:49], 15
	s_add_u32 s54, s2, s36
	s_addc_u32 s55, s19, s37
	s_and_b64 s[36:37], s[42:43], exec
	s_cselect_b32 s36, s55, s35
	s_cselect_b32 s37, s54, s34
	s_add_u32 s49, s34, 0x80000
	s_addc_u32 s97, s35, 0
	s_add_u32 s42, s56, 0x80
	v_mov_b32_e32 v4, 0
	s_addc_u32 s43, s57, 0
	s_mov_b32 s34, 0
	s_waitcnt lgkmcnt(0)
	v_mov_b32_e32 v5, v4
	v_mov_b32_e32 v6, v4
	v_mov_b32_e32 v7, v4
	v_mov_b32_e32 v8, v4
	v_mov_b32_e32 v9, v4
	v_mov_b32_e32 v10, v4
	v_mov_b32_e32 v11, v4
	v_mov_b32_e32 v20, v4
	v_mov_b32_e32 v21, v4
	v_mov_b32_e32 v22, v4
	v_mov_b32_e32 v23, v4
	v_mov_b32_e32 v24, v4
	v_mov_b32_e32 v25, v4
	v_mov_b32_e32 v26, v4
	v_mov_b32_e32 v27, v4
	v_mov_b32_e32 v36, v4
	v_mov_b32_e32 v37, v4
	v_mov_b32_e32 v38, v4
	v_mov_b32_e32 v39, v4
	v_mov_b32_e32 v40, v4
	v_mov_b32_e32 v41, v4
	v_mov_b32_e32 v42, v4
	v_mov_b32_e32 v43, v4
	v_mov_b32_e32 v52, v4
	v_mov_b32_e32 v53, v4
	v_mov_b32_e32 v54, v4
	v_mov_b32_e32 v55, v4
	v_mov_b32_e32 v56, v4
	v_mov_b32_e32 v57, v4
	v_mov_b32_e32 v58, v4
	v_mov_b32_e32 v59, v4
	v_mov_b32_e32 v12, v4
	v_mov_b32_e32 v13, v4
	v_mov_b32_e32 v14, v4
	v_mov_b32_e32 v15, v4
	v_mov_b32_e32 v16, v4
	v_mov_b32_e32 v17, v4
	v_mov_b32_e32 v18, v4
	v_mov_b32_e32 v19, v4
	v_mov_b32_e32 v28, v4
	v_mov_b32_e32 v29, v4
	v_mov_b32_e32 v30, v4
	v_mov_b32_e32 v31, v4
	v_mov_b32_e32 v32, v4
	v_mov_b32_e32 v33, v4
	v_mov_b32_e32 v34, v4
	v_mov_b32_e32 v35, v4
	v_mov_b32_e32 v44, v4
	v_mov_b32_e32 v45, v4
	v_mov_b32_e32 v46, v4
	v_mov_b32_e32 v47, v4
	v_mov_b32_e32 v48, v4
	v_mov_b32_e32 v49, v4
	v_mov_b32_e32 v50, v4
	v_mov_b32_e32 v51, v4
	v_mov_b32_e32 v60, v4
	v_mov_b32_e32 v61, v4
	v_mov_b32_e32 v62, v4
	v_mov_b32_e32 v63, v4
	v_mov_b32_e32 v64, v4
	v_mov_b32_e32 v65, v4
	v_mov_b32_e32 v66, v4
	v_mov_b32_e32 v67, v4
	v_mov_b32_e32 v68, v4
	v_mov_b32_e32 v69, v4
	v_mov_b32_e32 v70, v4
	v_mov_b32_e32 v71, v4
	v_mov_b32_e32 v72, v4
	v_mov_b32_e32 v73, v4
	v_mov_b32_e32 v74, v4
	v_mov_b32_e32 v75, v4
	v_mov_b32_e32 v84, v4
	v_mov_b32_e32 v85, v4
	v_mov_b32_e32 v86, v4
	v_mov_b32_e32 v87, v4
	v_mov_b32_e32 v88, v4
	v_mov_b32_e32 v89, v4
	v_mov_b32_e32 v90, v4
	v_mov_b32_e32 v91, v4
	v_mov_b32_e32 v100, v4
	v_mov_b32_e32 v101, v4
	v_mov_b32_e32 v102, v4
	v_mov_b32_e32 v103, v4
	v_mov_b32_e32 v104, v4
	v_mov_b32_e32 v105, v4
	v_mov_b32_e32 v106, v4
	v_mov_b32_e32 v107, v4
	v_mov_b32_e32 v128, v4
	v_mov_b32_e32 v129, v4
	v_mov_b32_e32 v130, v4
	v_mov_b32_e32 v131, v4
	v_mov_b32_e32 v132, v4
	v_mov_b32_e32 v133, v4
	v_mov_b32_e32 v134, v4
	v_mov_b32_e32 v135, v4
	v_mov_b32_e32 v76, v4
	v_mov_b32_e32 v77, v4
	v_mov_b32_e32 v78, v4
	v_mov_b32_e32 v79, v4
	v_mov_b32_e32 v80, v4
	v_mov_b32_e32 v81, v4
	v_mov_b32_e32 v82, v4
	v_mov_b32_e32 v83, v4
	v_mov_b32_e32 v92, v4
	v_mov_b32_e32 v93, v4
	v_mov_b32_e32 v94, v4
	v_mov_b32_e32 v95, v4
	v_mov_b32_e32 v96, v4
	v_mov_b32_e32 v97, v4
	v_mov_b32_e32 v98, v4
	v_mov_b32_e32 v99, v4
	v_mov_b32_e32 v108, v4
	v_mov_b32_e32 v109, v4
	v_mov_b32_e32 v110, v4
	v_mov_b32_e32 v111, v4
	v_mov_b32_e32 v112, v4
	v_mov_b32_e32 v113, v4
	v_mov_b32_e32 v114, v4
	v_mov_b32_e32 v115, v4
	v_mov_b32_e32 v140, v4
	v_mov_b32_e32 v141, v4
	v_mov_b32_e32 v142, v4
	v_mov_b32_e32 v143, v4
	v_mov_b32_e32 v144, v4
	v_mov_b32_e32 v145, v4
	v_mov_b32_e32 v146, v4
	v_mov_b32_e32 v147, v4
	v_readfirstlane_b32 s101, v156
	s_bfe_u32 s101, s101, 0x10008
	s_cmp_lg_u32 s101, 0
	s_cbranch_scc1 .Ltrail_3
.LBB0_559:
	s_add_i32 vcc_lo, s34, 2
	s_add_u32 s35, s42, 0x80
	s_addc_u32 s52, s43, 0
	s_add_i32 s53, 0, 0x10000
	s_cmp_eq_u32 s77, s34
	s_cselect_b32 s57, s51, s52
	s_cselect_b32 s56, s50, s35
	s_cselect_b32 s35, s36, s97
	s_cselect_b32 s34, s37, s49
	s_add_i32 s68, 0, 0x14000
	v_add_u32_e32 v136, s53, v200
	v_add_u32_e32 v186, s68, v200
	ds_read_b128 v[116:119], v136
	ds_read_b128 v[120:123], v136 offset:1024
	ds_read_b128 v[124:127], v136 offset:2048
	ds_read_b128 v[136:139], v136 offset:3072
	ds_read_b128 v[148:151], v186
	ds_read_b128 v[152:155], v186 offset:1024
	ds_read_b128 v[182:185], v186 offset:2048
	ds_read_b128 v[186:189], v186 offset:3072
	v_lshl_add_u64 v[198:199], s[42:43], 0, v[178:179]
	s_add_i32 m0, s59, 0xc000
	ds_read_b128 v[190:193], v202
	ds_read_b128 v[194:197], v202 offset:1024
	ds_read_b128 v[204:207], v202 offset:2048
	ds_read_b128 v[208:211], v202 offset:3072
	ds_read_b128 v[212:215], v202 offset:4096
	ds_read_b128 v[216:219], v202 offset:5120
	ds_read_b128 v[228:231], v202 offset:6144
	ds_read_b128 v[232:235], v202 offset:7168
	global_load_lds_dwordx4 v[198:199], off
	v_lshl_add_u64 v[198:199], s[42:43], 0, v[180:181]
	s_add_i32 m0, s59, 0xe000
	s_nop 0
	global_load_lds_dwordx4 v[198:199], off
	s_waitcnt lgkmcnt(0)
	s_barrier
	s_setprio 1
	v_mfma_f32_16x16x32_bf16 v[144:147], v[116:119], v[190:193], v[144:147]
	v_mfma_f32_16x16x32_bf16 v[144:147], v[120:123], v[194:197], v[144:147]
	v_mfma_f32_16x16x32_bf16 v[140:143], v[124:127], v[190:193], v[140:143]
	v_mfma_f32_16x16x32_bf16 v[140:143], v[136:139], v[194:197], v[140:143]
	v_mfma_f32_16x16x32_bf16 v[108:111], v[124:127], v[204:207], v[108:111]
	v_mfma_f32_16x16x32_bf16 v[108:111], v[136:139], v[208:211], v[108:111]
	v_mfma_f32_16x16x32_bf16 v[112:115], v[116:119], v[204:207], v[112:115]
	v_mfma_f32_16x16x32_bf16 v[112:115], v[120:123], v[208:211], v[112:115]
	v_mfma_f32_16x16x32_bf16 v[96:99], v[116:119], v[212:215], v[96:99]
	v_mfma_f32_16x16x32_bf16 v[96:99], v[120:123], v[216:219], v[96:99]
	v_mfma_f32_16x16x32_bf16 v[92:95], v[124:127], v[212:215], v[92:95]
	v_mfma_f32_16x16x32_bf16 v[92:95], v[136:139], v[216:219], v[92:95]
	v_mfma_f32_16x16x32_bf16 v[76:79], v[124:127], v[228:231], v[76:79]
	v_mfma_f32_16x16x32_bf16 v[76:79], v[136:139], v[232:235], v[76:79]
	v_mfma_f32_16x16x32_bf16 v[80:83], v[116:119], v[228:231], v[80:83]
	v_mfma_f32_16x16x32_bf16 v[80:83], v[120:123], v[232:235], v[80:83]
	v_mfma_f32_16x16x32_bf16 v[132:135], v[148:151], v[190:193], v[132:135]
	v_mfma_f32_16x16x32_bf16 v[132:135], v[152:155], v[194:197], v[132:135]
	v_mfma_f32_16x16x32_bf16 v[128:131], v[182:185], v[190:193], v[128:131]
	v_mfma_f32_16x16x32_bf16 v[128:131], v[186:189], v[194:197], v[128:131]
	v_mfma_f32_16x16x32_bf16 v[100:103], v[182:185], v[204:207], v[100:103]
	v_mfma_f32_16x16x32_bf16 v[100:103], v[186:189], v[208:211], v[100:103]
	v_mfma_f32_16x16x32_bf16 v[104:107], v[148:151], v[204:207], v[104:107]
	v_mfma_f32_16x16x32_bf16 v[104:107], v[152:155], v[208:211], v[104:107]
	v_mfma_f32_16x16x32_bf16 v[88:91], v[148:151], v[212:215], v[88:91]
	v_mfma_f32_16x16x32_bf16 v[88:91], v[152:155], v[216:219], v[88:91]
	v_mfma_f32_16x16x32_bf16 v[84:87], v[182:185], v[212:215], v[84:87]
	v_mfma_f32_16x16x32_bf16 v[84:87], v[186:189], v[216:219], v[84:87]
	v_mfma_f32_16x16x32_bf16 v[68:71], v[182:185], v[228:231], v[68:71]
	v_mfma_f32_16x16x32_bf16 v[68:71], v[186:189], v[232:235], v[68:71]
	v_mfma_f32_16x16x32_bf16 v[72:75], v[148:151], v[228:231], v[72:75]
	v_mfma_f32_16x16x32_bf16 v[72:75], v[152:155], v[232:235], v[72:75]
	s_setprio 0
	s_waitcnt vmcnt(8)
	s_barrier
	s_add_i32 s52, s53, s58
	v_lshl_add_u64 v[198:199], s[34:35], 0, v[174:175]
	s_mov_b32 m0, s52
	ds_read_b128 v[190:193], v202 offset:16384
	ds_read_b128 v[194:197], v202 offset:17408
	ds_read_b128 v[204:207], v202 offset:18432
	ds_read_b128 v[208:211], v202 offset:19456
	ds_read_b128 v[212:215], v202 offset:20480
	ds_read_b128 v[216:219], v202 offset:21504
	ds_read_b128 v[228:231], v202 offset:22528
	ds_read_b128 v[232:235], v202 offset:23552
	global_load_lds_dwordx4 v[198:199], off
	s_add_i32 m0, s52, 0x2000
	s_add_u32 s52, s34, 0x4000
	v_lshl_add_u64 v[198:199], s[34:35], 0, v[0:1]
	s_addc_u32 s53, s35, 0
	s_add_i32 s68, s68, s58
	global_load_lds_dwordx4 v[198:199], off
	v_lshl_add_u64 v[198:199], s[52:53], 0, v[174:175]
	s_mov_b32 m0, s68
	v_lshl_add_u64 v[236:237], s[56:57], 0, v[172:173]
	global_load_lds_dwordx4 v[198:199], off
	v_lshl_add_u64 v[198:199], s[52:53], 0, v[0:1]
	s_add_i32 m0, s68, 0x2000
	s_nop 0
	global_load_lds_dwordx4 v[198:199], off
	v_lshl_add_u64 v[198:199], s[56:57], 0, v[176:177]
	s_mov_b32 m0, s59
	s_nop 0
	global_load_lds_dwordx4 v[198:199], off
	s_mov_b32 m0, s60
	s_nop 0
	global_load_lds_dwordx4 v[236:237], off
	s_waitcnt lgkmcnt(0)
	s_barrier
	s_setprio 1
	v_mfma_f32_16x16x32_bf16 v[64:67], v[116:119], v[190:193], v[64:67]
	v_mfma_f32_16x16x32_bf16 v[64:67], v[120:123], v[194:197], v[64:67]
	v_mfma_f32_16x16x32_bf16 v[60:63], v[124:127], v[190:193], v[60:63]
	v_mfma_f32_16x16x32_bf16 v[60:63], v[136:139], v[194:197], v[60:63]
	v_mfma_f32_16x16x32_bf16 v[44:47], v[124:127], v[204:207], v[44:47]
	v_mfma_f32_16x16x32_bf16 v[44:47], v[136:139], v[208:211], v[44:47]
	v_mfma_f32_16x16x32_bf16 v[48:51], v[116:119], v[204:207], v[48:51]
	v_mfma_f32_16x16x32_bf16 v[48:51], v[120:123], v[208:211], v[48:51]
	v_mfma_f32_16x16x32_bf16 v[32:35], v[116:119], v[212:215], v[32:35]
	v_mfma_f32_16x16x32_bf16 v[32:35], v[120:123], v[216:219], v[32:35]
	v_mfma_f32_16x16x32_bf16 v[28:31], v[124:127], v[212:215], v[28:31]
	v_mfma_f32_16x16x32_bf16 v[28:31], v[136:139], v[216:219], v[28:31]
	v_mfma_f32_16x16x32_bf16 v[12:15], v[124:127], v[228:231], v[12:15]
	v_mfma_f32_16x16x32_bf16 v[12:15], v[136:139], v[232:235], v[12:15]
	v_mfma_f32_16x16x32_bf16 v[16:19], v[116:119], v[228:231], v[16:19]
	v_mfma_f32_16x16x32_bf16 v[16:19], v[120:123], v[232:235], v[16:19]
	v_mfma_f32_16x16x32_bf16 v[56:59], v[148:151], v[190:193], v[56:59]
	v_mfma_f32_16x16x32_bf16 v[56:59], v[152:155], v[194:197], v[56:59]
	v_mfma_f32_16x16x32_bf16 v[52:55], v[182:185], v[190:193], v[52:55]
	v_mfma_f32_16x16x32_bf16 v[52:55], v[186:189], v[194:197], v[52:55]
	v_mfma_f32_16x16x32_bf16 v[36:39], v[182:185], v[204:207], v[36:39]
	v_mfma_f32_16x16x32_bf16 v[36:39], v[186:189], v[208:211], v[36:39]
	v_mfma_f32_16x16x32_bf16 v[40:43], v[148:151], v[204:207], v[40:43]
	v_mfma_f32_16x16x32_bf16 v[40:43], v[152:155], v[208:211], v[40:43]
	v_mfma_f32_16x16x32_bf16 v[24:27], v[148:151], v[212:215], v[24:27]
	v_mfma_f32_16x16x32_bf16 v[24:27], v[152:155], v[216:219], v[24:27]
	v_mfma_f32_16x16x32_bf16 v[20:23], v[182:185], v[212:215], v[20:23]
	v_mfma_f32_16x16x32_bf16 v[20:23], v[186:189], v[216:219], v[20:23]
	v_mfma_f32_16x16x32_bf16 v[4:7], v[182:185], v[228:231], v[4:7]
	v_mfma_f32_16x16x32_bf16 v[4:7], v[186:189], v[232:235], v[4:7]
	v_mfma_f32_16x16x32_bf16 v[8:11], v[148:151], v[228:231], v[8:11]
	v_mfma_f32_16x16x32_bf16 v[8:11], v[152:155], v[232:235], v[8:11]
	s_setprio 0
	s_waitcnt vmcnt(8)
	s_barrier
	s_add_i32 s68, 0, 0x18000
	s_add_i32 vcc_hi, 0, 0x1c000
	v_add_u32_e32 v136, s68, v200
	v_add_u32_e32 v186, vcc_hi, v200
	ds_read_b128 v[116:119], v136
	ds_read_b128 v[120:123], v136 offset:1024
	ds_read_b128 v[124:127], v136 offset:2048
	ds_read_b128 v[136:139], v136 offset:3072
	ds_read_b128 v[148:151], v186
	ds_read_b128 v[152:155], v186 offset:1024
	ds_read_b128 v[182:185], v186 offset:2048
	ds_read_b128 v[186:189], v186 offset:3072
	s_add_u32 s52, s56, s26
	s_addc_u32 s53, s57, 0
	s_mov_b32 m0, s61
	v_lshl_add_u64 v[238:239], s[52:53], 0, v[176:177]
	ds_read_b128 v[190:193], v202 offset:32768
	ds_read_b128 v[194:197], v202 offset:33792
	ds_read_b128 v[204:207], v202 offset:34816
	ds_read_b128 v[208:211], v202 offset:35840
	ds_read_b128 v[212:215], v202 offset:36864
	ds_read_b128 v[216:219], v202 offset:37888
	ds_read_b128 v[228:231], v202 offset:38912
	ds_read_b128 v[232:235], v202 offset:39936
	global_load_lds_dwordx4 v[238:239], off
	v_lshl_add_u64 v[238:239], s[52:53], 0, v[172:173]
	s_mov_b32 m0, s62
	s_nop 0
	global_load_lds_dwordx4 v[238:239], off
	s_waitcnt lgkmcnt(0)
	s_barrier
	s_setprio 1
	v_mfma_f32_16x16x32_bf16 v[144:147], v[116:119], v[190:193], v[144:147]
	v_mfma_f32_16x16x32_bf16 v[144:147], v[120:123], v[194:197], v[144:147]
	v_mfma_f32_16x16x32_bf16 v[140:143], v[124:127], v[190:193], v[140:143]
	v_mfma_f32_16x16x32_bf16 v[140:143], v[136:139], v[194:197], v[140:143]
	v_mfma_f32_16x16x32_bf16 v[108:111], v[124:127], v[204:207], v[108:111]
	v_mfma_f32_16x16x32_bf16 v[108:111], v[136:139], v[208:211], v[108:111]
	v_mfma_f32_16x16x32_bf16 v[112:115], v[116:119], v[204:207], v[112:115]
	v_mfma_f32_16x16x32_bf16 v[112:115], v[120:123], v[208:211], v[112:115]
	v_mfma_f32_16x16x32_bf16 v[96:99], v[116:119], v[212:215], v[96:99]
	v_mfma_f32_16x16x32_bf16 v[96:99], v[120:123], v[216:219], v[96:99]
	v_mfma_f32_16x16x32_bf16 v[92:95], v[124:127], v[212:215], v[92:95]
	v_mfma_f32_16x16x32_bf16 v[92:95], v[136:139], v[216:219], v[92:95]
	v_mfma_f32_16x16x32_bf16 v[76:79], v[124:127], v[228:231], v[76:79]
	v_mfma_f32_16x16x32_bf16 v[76:79], v[136:139], v[232:235], v[76:79]
	v_mfma_f32_16x16x32_bf16 v[80:83], v[116:119], v[228:231], v[80:83]
	v_mfma_f32_16x16x32_bf16 v[80:83], v[120:123], v[232:235], v[80:83]
	v_mfma_f32_16x16x32_bf16 v[132:135], v[148:151], v[190:193], v[132:135]
	v_mfma_f32_16x16x32_bf16 v[132:135], v[152:155], v[194:197], v[132:135]
	v_mfma_f32_16x16x32_bf16 v[128:131], v[182:185], v[190:193], v[128:131]
	v_mfma_f32_16x16x32_bf16 v[128:131], v[186:189], v[194:197], v[128:131]
	v_mfma_f32_16x16x32_bf16 v[100:103], v[182:185], v[204:207], v[100:103]
	v_mfma_f32_16x16x32_bf16 v[100:103], v[186:189], v[208:211], v[100:103]
	v_mfma_f32_16x16x32_bf16 v[104:107], v[148:151], v[204:207], v[104:107]
	v_mfma_f32_16x16x32_bf16 v[104:107], v[152:155], v[208:211], v[104:107]
	v_mfma_f32_16x16x32_bf16 v[88:91], v[148:151], v[212:215], v[88:91]
	v_mfma_f32_16x16x32_bf16 v[88:91], v[152:155], v[216:219], v[88:91]
	v_mfma_f32_16x16x32_bf16 v[84:87], v[182:185], v[212:215], v[84:87]
	v_mfma_f32_16x16x32_bf16 v[84:87], v[186:189], v[216:219], v[84:87]
	v_mfma_f32_16x16x32_bf16 v[68:71], v[182:185], v[228:231], v[68:71]
	v_mfma_f32_16x16x32_bf16 v[68:71], v[186:189], v[232:235], v[68:71]
	v_mfma_f32_16x16x32_bf16 v[72:75], v[148:151], v[228:231], v[72:75]
	v_mfma_f32_16x16x32_bf16 v[72:75], v[152:155], v[232:235], v[72:75]
	s_setprio 0
	s_waitcnt vmcnt(8)
	s_barrier
	s_add_u32 s52, s34, 0x40000
	s_addc_u32 s53, s35, 0
	s_add_i32 s56, s68, s58
	v_lshl_add_u64 v[238:239], s[52:53], 0, v[174:175]
	s_mov_b32 m0, s56
	ds_read_b128 v[190:193], v202 offset:49152
	ds_read_b128 v[194:197], v202 offset:50176
	ds_read_b128 v[204:207], v202 offset:51200
	ds_read_b128 v[208:211], v202 offset:52224
	ds_read_b128 v[212:215], v202 offset:53248
	ds_read_b128 v[216:219], v202 offset:54272
	ds_read_b128 v[228:231], v202 offset:55296
	ds_read_b128 v[232:235], v202 offset:56320
	global_load_lds_dwordx4 v[238:239], off
	s_add_i32 m0, s56, 0x2000
	s_add_u32 s34, s34, 0x44000
	v_lshl_add_u64 v[238:239], s[52:53], 0, v[0:1]
	s_addc_u32 s35, s35, 0
	s_add_i32 s52, vcc_hi, s58
	global_load_lds_dwordx4 v[238:239], off
	v_lshl_add_u64 v[238:239], s[34:35], 0, v[174:175]
	s_mov_b32 m0, s52
	v_lshl_add_u64 v[198:199], v[198:199], 0, s[14:15]
	global_load_lds_dwordx4 v[238:239], off
	v_lshl_add_u64 v[238:239], s[34:35], 0, v[0:1]
	s_add_i32 m0, s52, 0x2000
	s_nop 0
	global_load_lds_dwordx4 v[238:239], off
	s_mov_b32 m0, s71
	s_nop 0
	global_load_lds_dwordx4 v[198:199], off
	v_lshl_add_u64 v[198:199], v[236:237], 0, s[14:15]
	s_mov_b32 m0, s76
	s_nop 0
	global_load_lds_dwordx4 v[198:199], off
	s_waitcnt lgkmcnt(0)
	s_barrier
	s_setprio 1
	v_mfma_f32_16x16x32_bf16 v[64:67], v[116:119], v[190:193], v[64:67]
	v_mfma_f32_16x16x32_bf16 v[64:67], v[120:123], v[194:197], v[64:67]
	v_mfma_f32_16x16x32_bf16 v[60:63], v[124:127], v[190:193], v[60:63]
	v_mfma_f32_16x16x32_bf16 v[60:63], v[136:139], v[194:197], v[60:63]
	v_mfma_f32_16x16x32_bf16 v[44:47], v[124:127], v[204:207], v[44:47]
	v_mfma_f32_16x16x32_bf16 v[44:47], v[136:139], v[208:211], v[44:47]
	v_mfma_f32_16x16x32_bf16 v[48:51], v[116:119], v[204:207], v[48:51]
	v_mfma_f32_16x16x32_bf16 v[48:51], v[120:123], v[208:211], v[48:51]
	v_mfma_f32_16x16x32_bf16 v[32:35], v[116:119], v[212:215], v[32:35]
	v_mfma_f32_16x16x32_bf16 v[32:35], v[120:123], v[216:219], v[32:35]
	v_mfma_f32_16x16x32_bf16 v[28:31], v[124:127], v[212:215], v[28:31]
	v_mfma_f32_16x16x32_bf16 v[28:31], v[136:139], v[216:219], v[28:31]
	v_mfma_f32_16x16x32_bf16 v[12:15], v[124:127], v[228:231], v[12:15]
	v_mfma_f32_16x16x32_bf16 v[12:15], v[136:139], v[232:235], v[12:15]
	v_mfma_f32_16x16x32_bf16 v[16:19], v[116:119], v[228:231], v[16:19]
	v_mfma_f32_16x16x32_bf16 v[16:19], v[120:123], v[232:235], v[16:19]
	v_mfma_f32_16x16x32_bf16 v[56:59], v[148:151], v[190:193], v[56:59]
	v_mfma_f32_16x16x32_bf16 v[56:59], v[152:155], v[194:197], v[56:59]
	v_mfma_f32_16x16x32_bf16 v[52:55], v[182:185], v[190:193], v[52:55]
	v_mfma_f32_16x16x32_bf16 v[52:55], v[186:189], v[194:197], v[52:55]
	v_mfma_f32_16x16x32_bf16 v[36:39], v[182:185], v[204:207], v[36:39]
	v_mfma_f32_16x16x32_bf16 v[36:39], v[186:189], v[208:211], v[36:39]
	v_mfma_f32_16x16x32_bf16 v[40:43], v[148:151], v[204:207], v[40:43]
	v_mfma_f32_16x16x32_bf16 v[40:43], v[152:155], v[208:211], v[40:43]
	v_mfma_f32_16x16x32_bf16 v[24:27], v[148:151], v[212:215], v[24:27]
	v_mfma_f32_16x16x32_bf16 v[24:27], v[152:155], v[216:219], v[24:27]
	v_mfma_f32_16x16x32_bf16 v[20:23], v[182:185], v[212:215], v[20:23]
	v_mfma_f32_16x16x32_bf16 v[20:23], v[186:189], v[216:219], v[20:23]
	v_mfma_f32_16x16x32_bf16 v[4:7], v[182:185], v[228:231], v[4:7]
	v_mfma_f32_16x16x32_bf16 v[4:7], v[186:189], v[232:235], v[4:7]
	v_mfma_f32_16x16x32_bf16 v[8:11], v[148:151], v[228:231], v[8:11]
	v_mfma_f32_16x16x32_bf16 v[8:11], v[152:155], v[232:235], v[8:11]
	s_setprio 0
	s_waitcnt vmcnt(8)
	s_barrier
	s_add_u32 s49, s49, 0x80000
	s_addc_u32 s97, s97, 0
	s_add_u32 s42, s42, 0x100
	s_addc_u32 s43, s43, 0
	s_cmp_ge_u32 vcc_lo, s69
	s_mov_b32 s34, vcc_lo
	s_cbranch_scc0 .LBB0_559
	s_branch .Lkdone_3
.Ltrail_3:
	s_add_i32 vcc_lo, s34, 2
	s_add_u32 s35, s42, 0x80
	s_addc_u32 s52, s43, 0
	s_add_i32 s53, 0, 0x10000
	s_cmp_eq_u32 s77, s34
	s_cselect_b32 s57, s51, s52
	s_cselect_b32 s56, s50, s35
	s_cselect_b32 s35, s36, s97
	s_cselect_b32 s34, s37, s49
	s_add_i32 s68, 0, 0x14000
	v_add_u32_e32 v136, s53, v200
	v_add_u32_e32 v186, s68, v200
	ds_read_b128 v[116:119], v136
	ds_read_b128 v[120:123], v136 offset:1024
	ds_read_b128 v[124:127], v136 offset:2048
	ds_read_b128 v[136:139], v136 offset:3072
	ds_read_b128 v[148:151], v186
	ds_read_b128 v[152:155], v186 offset:1024
	ds_read_b128 v[182:185], v186 offset:2048
	ds_read_b128 v[186:189], v186 offset:3072
	v_lshl_add_u64 v[198:199], s[42:43], 0, v[178:179]
	s_add_i32 m0, s59, 0xc000
	ds_read_b128 v[190:193], v202
	ds_read_b128 v[194:197], v202 offset:1024
	ds_read_b128 v[204:207], v202 offset:2048
	ds_read_b128 v[208:211], v202 offset:3072
	ds_read_b128 v[212:215], v202 offset:4096
	ds_read_b128 v[216:219], v202 offset:5120
	ds_read_b128 v[228:231], v202 offset:6144
	ds_read_b128 v[232:235], v202 offset:7168
	global_load_lds_dwordx4 v[198:199], off
	v_lshl_add_u64 v[198:199], s[42:43], 0, v[180:181]
	s_add_i32 m0, s59, 0xe000
	s_nop 0
	global_load_lds_dwordx4 v[198:199], off
	s_waitcnt vmcnt(8)
	s_waitcnt lgkmcnt(0)
	s_barrier
	s_setprio 1
	v_mfma_f32_16x16x32_bf16 v[144:147], v[116:119], v[190:193], v[144:147]
	v_mfma_f32_16x16x32_bf16 v[144:147], v[120:123], v[194:197], v[144:147]
	v_mfma_f32_16x16x32_bf16 v[140:143], v[124:127], v[190:193], v[140:143]
	v_mfma_f32_16x16x32_bf16 v[140:143], v[136:139], v[194:197], v[140:143]
	v_mfma_f32_16x16x32_bf16 v[108:111], v[124:127], v[204:207], v[108:111]
	v_mfma_f32_16x16x32_bf16 v[108:111], v[136:139], v[208:211], v[108:111]
	v_mfma_f32_16x16x32_bf16 v[112:115], v[116:119], v[204:207], v[112:115]
	v_mfma_f32_16x16x32_bf16 v[112:115], v[120:123], v[208:211], v[112:115]
	v_mfma_f32_16x16x32_bf16 v[96:99], v[116:119], v[212:215], v[96:99]
	v_mfma_f32_16x16x32_bf16 v[96:99], v[120:123], v[216:219], v[96:99]
	v_mfma_f32_16x16x32_bf16 v[92:95], v[124:127], v[212:215], v[92:95]
	v_mfma_f32_16x16x32_bf16 v[92:95], v[136:139], v[216:219], v[92:95]
	v_mfma_f32_16x16x32_bf16 v[76:79], v[124:127], v[228:231], v[76:79]
	v_mfma_f32_16x16x32_bf16 v[76:79], v[136:139], v[232:235], v[76:79]
	v_mfma_f32_16x16x32_bf16 v[80:83], v[116:119], v[228:231], v[80:83]
	v_mfma_f32_16x16x32_bf16 v[80:83], v[120:123], v[232:235], v[80:83]
	v_mfma_f32_16x16x32_bf16 v[132:135], v[148:151], v[190:193], v[132:135]
	v_mfma_f32_16x16x32_bf16 v[132:135], v[152:155], v[194:197], v[132:135]
	v_mfma_f32_16x16x32_bf16 v[128:131], v[182:185], v[190:193], v[128:131]
	v_mfma_f32_16x16x32_bf16 v[128:131], v[186:189], v[194:197], v[128:131]
	v_mfma_f32_16x16x32_bf16 v[100:103], v[182:185], v[204:207], v[100:103]
	v_mfma_f32_16x16x32_bf16 v[100:103], v[186:189], v[208:211], v[100:103]
	v_mfma_f32_16x16x32_bf16 v[104:107], v[148:151], v[204:207], v[104:107]
	v_mfma_f32_16x16x32_bf16 v[104:107], v[152:155], v[208:211], v[104:107]
	v_mfma_f32_16x16x32_bf16 v[88:91], v[148:151], v[212:215], v[88:91]
	v_mfma_f32_16x16x32_bf16 v[88:91], v[152:155], v[216:219], v[88:91]
	v_mfma_f32_16x16x32_bf16 v[84:87], v[182:185], v[212:215], v[84:87]
	v_mfma_f32_16x16x32_bf16 v[84:87], v[186:189], v[216:219], v[84:87]
	v_mfma_f32_16x16x32_bf16 v[68:71], v[182:185], v[228:231], v[68:71]
	v_mfma_f32_16x16x32_bf16 v[68:71], v[186:189], v[232:235], v[68:71]
	v_mfma_f32_16x16x32_bf16 v[72:75], v[148:151], v[228:231], v[72:75]
	v_mfma_f32_16x16x32_bf16 v[72:75], v[152:155], v[232:235], v[72:75]
	s_setprio 0
	s_barrier
	s_add_i32 s52, s53, s58
	v_lshl_add_u64 v[198:199], s[34:35], 0, v[174:175]
	s_mov_b32 m0, s52
	ds_read_b128 v[190:193], v202 offset:16384
	ds_read_b128 v[194:197], v202 offset:17408
	ds_read_b128 v[204:207], v202 offset:18432
	ds_read_b128 v[208:211], v202 offset:19456
	ds_read_b128 v[212:215], v202 offset:20480
	ds_read_b128 v[216:219], v202 offset:21504
	ds_read_b128 v[228:231], v202 offset:22528
	ds_read_b128 v[232:235], v202 offset:23552
	global_load_lds_dwordx4 v[198:199], off
	s_add_i32 m0, s52, 0x2000
	s_add_u32 s52, s34, 0x4000
	v_lshl_add_u64 v[198:199], s[34:35], 0, v[0:1]
	s_addc_u32 s53, s35, 0
	s_add_i32 s68, s68, s58
	global_load_lds_dwordx4 v[198:199], off
	v_lshl_add_u64 v[198:199], s[52:53], 0, v[174:175]
	s_mov_b32 m0, s68
	v_lshl_add_u64 v[236:237], s[56:57], 0, v[172:173]
	global_load_lds_dwordx4 v[198:199], off
	v_lshl_add_u64 v[198:199], s[52:53], 0, v[0:1]
	s_add_i32 m0, s68, 0x2000
	s_nop 0
	global_load_lds_dwordx4 v[198:199], off
	v_lshl_add_u64 v[198:199], s[56:57], 0, v[176:177]
	s_mov_b32 m0, s59
	s_nop 0
	global_load_lds_dwordx4 v[198:199], off
	s_mov_b32 m0, s60
	s_nop 0
	global_load_lds_dwordx4 v[236:237], off
	s_waitcnt vmcnt(8)
	s_waitcnt lgkmcnt(0)
	s_barrier
	s_setprio 1
	v_mfma_f32_16x16x32_bf16 v[64:67], v[116:119], v[190:193], v[64:67]
	v_mfma_f32_16x16x32_bf16 v[64:67], v[120:123], v[194:197], v[64:67]
	v_mfma_f32_16x16x32_bf16 v[60:63], v[124:127], v[190:193], v[60:63]
	v_mfma_f32_16x16x32_bf16 v[60:63], v[136:139], v[194:197], v[60:63]
	v_mfma_f32_16x16x32_bf16 v[44:47], v[124:127], v[204:207], v[44:47]
	v_mfma_f32_16x16x32_bf16 v[44:47], v[136:139], v[208:211], v[44:47]
	v_mfma_f32_16x16x32_bf16 v[48:51], v[116:119], v[204:207], v[48:51]
	v_mfma_f32_16x16x32_bf16 v[48:51], v[120:123], v[208:211], v[48:51]
	v_mfma_f32_16x16x32_bf16 v[32:35], v[116:119], v[212:215], v[32:35]
	v_mfma_f32_16x16x32_bf16 v[32:35], v[120:123], v[216:219], v[32:35]
	v_mfma_f32_16x16x32_bf16 v[28:31], v[124:127], v[212:215], v[28:31]
	v_mfma_f32_16x16x32_bf16 v[28:31], v[136:139], v[216:219], v[28:31]
	v_mfma_f32_16x16x32_bf16 v[12:15], v[124:127], v[228:231], v[12:15]
	v_mfma_f32_16x16x32_bf16 v[12:15], v[136:139], v[232:235], v[12:15]
	v_mfma_f32_16x16x32_bf16 v[16:19], v[116:119], v[228:231], v[16:19]
	v_mfma_f32_16x16x32_bf16 v[16:19], v[120:123], v[232:235], v[16:19]
	v_mfma_f32_16x16x32_bf16 v[56:59], v[148:151], v[190:193], v[56:59]
	v_mfma_f32_16x16x32_bf16 v[56:59], v[152:155], v[194:197], v[56:59]
	v_mfma_f32_16x16x32_bf16 v[52:55], v[182:185], v[190:193], v[52:55]
	v_mfma_f32_16x16x32_bf16 v[52:55], v[186:189], v[194:197], v[52:55]
	v_mfma_f32_16x16x32_bf16 v[36:39], v[182:185], v[204:207], v[36:39]
	v_mfma_f32_16x16x32_bf16 v[36:39], v[186:189], v[208:211], v[36:39]
	v_mfma_f32_16x16x32_bf16 v[40:43], v[148:151], v[204:207], v[40:43]
	v_mfma_f32_16x16x32_bf16 v[40:43], v[152:155], v[208:211], v[40:43]
	v_mfma_f32_16x16x32_bf16 v[24:27], v[148:151], v[212:215], v[24:27]
	v_mfma_f32_16x16x32_bf16 v[24:27], v[152:155], v[216:219], v[24:27]
	v_mfma_f32_16x16x32_bf16 v[20:23], v[182:185], v[212:215], v[20:23]
	v_mfma_f32_16x16x32_bf16 v[20:23], v[186:189], v[216:219], v[20:23]
	v_mfma_f32_16x16x32_bf16 v[4:7], v[182:185], v[228:231], v[4:7]
	v_mfma_f32_16x16x32_bf16 v[4:7], v[186:189], v[232:235], v[4:7]
	v_mfma_f32_16x16x32_bf16 v[8:11], v[148:151], v[228:231], v[8:11]
	v_mfma_f32_16x16x32_bf16 v[8:11], v[152:155], v[232:235], v[8:11]
	s_setprio 0
	s_barrier
	s_add_i32 s68, 0, 0x18000
	s_add_i32 vcc_hi, 0, 0x1c000
	v_add_u32_e32 v136, s68, v200
	v_add_u32_e32 v186, vcc_hi, v200
	ds_read_b128 v[116:119], v136
	ds_read_b128 v[120:123], v136 offset:1024
	ds_read_b128 v[124:127], v136 offset:2048
	ds_read_b128 v[136:139], v136 offset:3072
	ds_read_b128 v[148:151], v186
	ds_read_b128 v[152:155], v186 offset:1024
	ds_read_b128 v[182:185], v186 offset:2048
	ds_read_b128 v[186:189], v186 offset:3072
	s_add_u32 s52, s56, s26
	s_addc_u32 s53, s57, 0
	s_mov_b32 m0, s61
	v_lshl_add_u64 v[238:239], s[52:53], 0, v[176:177]
	ds_read_b128 v[190:193], v202 offset:32768
	ds_read_b128 v[194:197], v202 offset:33792
	ds_read_b128 v[204:207], v202 offset:34816
	ds_read_b128 v[208:211], v202 offset:35840
	ds_read_b128 v[212:215], v202 offset:36864
	ds_read_b128 v[216:219], v202 offset:37888
	ds_read_b128 v[228:231], v202 offset:38912
	ds_read_b128 v[232:235], v202 offset:39936
	global_load_lds_dwordx4 v[238:239], off
	v_lshl_add_u64 v[238:239], s[52:53], 0, v[172:173]
	s_mov_b32 m0, s62
	s_nop 0
	global_load_lds_dwordx4 v[238:239], off
	s_waitcnt vmcnt(8)
	s_waitcnt lgkmcnt(0)
	s_barrier
	s_setprio 1
	v_mfma_f32_16x16x32_bf16 v[144:147], v[116:119], v[190:193], v[144:147]
	v_mfma_f32_16x16x32_bf16 v[144:147], v[120:123], v[194:197], v[144:147]
	v_mfma_f32_16x16x32_bf16 v[140:143], v[124:127], v[190:193], v[140:143]
	v_mfma_f32_16x16x32_bf16 v[140:143], v[136:139], v[194:197], v[140:143]
	v_mfma_f32_16x16x32_bf16 v[108:111], v[124:127], v[204:207], v[108:111]
	v_mfma_f32_16x16x32_bf16 v[108:111], v[136:139], v[208:211], v[108:111]
	v_mfma_f32_16x16x32_bf16 v[112:115], v[116:119], v[204:207], v[112:115]
	v_mfma_f32_16x16x32_bf16 v[112:115], v[120:123], v[208:211], v[112:115]
	v_mfma_f32_16x16x32_bf16 v[96:99], v[116:119], v[212:215], v[96:99]
	v_mfma_f32_16x16x32_bf16 v[96:99], v[120:123], v[216:219], v[96:99]
	v_mfma_f32_16x16x32_bf16 v[92:95], v[124:127], v[212:215], v[92:95]
	v_mfma_f32_16x16x32_bf16 v[92:95], v[136:139], v[216:219], v[92:95]
	v_mfma_f32_16x16x32_bf16 v[76:79], v[124:127], v[228:231], v[76:79]
	v_mfma_f32_16x16x32_bf16 v[76:79], v[136:139], v[232:235], v[76:79]
	v_mfma_f32_16x16x32_bf16 v[80:83], v[116:119], v[228:231], v[80:83]
	v_mfma_f32_16x16x32_bf16 v[80:83], v[120:123], v[232:235], v[80:83]
	v_mfma_f32_16x16x32_bf16 v[132:135], v[148:151], v[190:193], v[132:135]
	v_mfma_f32_16x16x32_bf16 v[132:135], v[152:155], v[194:197], v[132:135]
	v_mfma_f32_16x16x32_bf16 v[128:131], v[182:185], v[190:193], v[128:131]
	v_mfma_f32_16x16x32_bf16 v[128:131], v[186:189], v[194:197], v[128:131]
	v_mfma_f32_16x16x32_bf16 v[100:103], v[182:185], v[204:207], v[100:103]
	v_mfma_f32_16x16x32_bf16 v[100:103], v[186:189], v[208:211], v[100:103]
	v_mfma_f32_16x16x32_bf16 v[104:107], v[148:151], v[204:207], v[104:107]
	v_mfma_f32_16x16x32_bf16 v[104:107], v[152:155], v[208:211], v[104:107]
	v_mfma_f32_16x16x32_bf16 v[88:91], v[148:151], v[212:215], v[88:91]
	v_mfma_f32_16x16x32_bf16 v[88:91], v[152:155], v[216:219], v[88:91]
	v_mfma_f32_16x16x32_bf16 v[84:87], v[182:185], v[212:215], v[84:87]
	v_mfma_f32_16x16x32_bf16 v[84:87], v[186:189], v[216:219], v[84:87]
	v_mfma_f32_16x16x32_bf16 v[68:71], v[182:185], v[228:231], v[68:71]
	v_mfma_f32_16x16x32_bf16 v[68:71], v[186:189], v[232:235], v[68:71]
	v_mfma_f32_16x16x32_bf16 v[72:75], v[148:151], v[228:231], v[72:75]
	v_mfma_f32_16x16x32_bf16 v[72:75], v[152:155], v[232:235], v[72:75]
	s_setprio 0
	s_barrier
	s_add_u32 s52, s34, 0x40000
	s_addc_u32 s53, s35, 0
	s_add_i32 s56, s68, s58
	v_lshl_add_u64 v[238:239], s[52:53], 0, v[174:175]
	s_mov_b32 m0, s56
	ds_read_b128 v[190:193], v202 offset:49152
	ds_read_b128 v[194:197], v202 offset:50176
	ds_read_b128 v[204:207], v202 offset:51200
	ds_read_b128 v[208:211], v202 offset:52224
	ds_read_b128 v[212:215], v202 offset:53248
	ds_read_b128 v[216:219], v202 offset:54272
	ds_read_b128 v[228:231], v202 offset:55296
	ds_read_b128 v[232:235], v202 offset:56320
	global_load_lds_dwordx4 v[238:239], off
	s_add_i32 m0, s56, 0x2000
	s_add_u32 s34, s34, 0x44000
	v_lshl_add_u64 v[238:239], s[52:53], 0, v[0:1]
	s_addc_u32 s35, s35, 0
	s_add_i32 s52, vcc_hi, s58
	global_load_lds_dwordx4 v[238:239], off
	v_lshl_add_u64 v[238:239], s[34:35], 0, v[174:175]
	s_mov_b32 m0, s52
	v_lshl_add_u64 v[198:199], v[198:199], 0, s[14:15]
	global_load_lds_dwordx4 v[238:239], off
	v_lshl_add_u64 v[238:239], s[34:35], 0, v[0:1]
	s_add_i32 m0, s52, 0x2000
	s_nop 0
	global_load_lds_dwordx4 v[238:239], off
	s_mov_b32 m0, s71
	s_nop 0
	global_load_lds_dwordx4 v[198:199], off
	v_lshl_add_u64 v[198:199], v[236:237], 0, s[14:15]
	s_mov_b32 m0, s76
	s_nop 0
	global_load_lds_dwordx4 v[198:199], off
	s_waitcnt vmcnt(8)
	s_waitcnt lgkmcnt(0)
	s_barrier
	s_setprio 1
	v_mfma_f32_16x16x32_bf16 v[64:67], v[116:119], v[190:193], v[64:67]
	v_mfma_f32_16x16x32_bf16 v[64:67], v[120:123], v[194:197], v[64:67]
	v_mfma_f32_16x16x32_bf16 v[60:63], v[124:127], v[190:193], v[60:63]
	v_mfma_f32_16x16x32_bf16 v[60:63], v[136:139], v[194:197], v[60:63]
	v_mfma_f32_16x16x32_bf16 v[44:47], v[124:127], v[204:207], v[44:47]
	v_mfma_f32_16x16x32_bf16 v[44:47], v[136:139], v[208:211], v[44:47]
	v_mfma_f32_16x16x32_bf16 v[48:51], v[116:119], v[204:207], v[48:51]
	v_mfma_f32_16x16x32_bf16 v[48:51], v[120:123], v[208:211], v[48:51]
	v_mfma_f32_16x16x32_bf16 v[32:35], v[116:119], v[212:215], v[32:35]
	v_mfma_f32_16x16x32_bf16 v[32:35], v[120:123], v[216:219], v[32:35]
	v_mfma_f32_16x16x32_bf16 v[28:31], v[124:127], v[212:215], v[28:31]
	v_mfma_f32_16x16x32_bf16 v[28:31], v[136:139], v[216:219], v[28:31]
	v_mfma_f32_16x16x32_bf16 v[12:15], v[124:127], v[228:231], v[12:15]
	v_mfma_f32_16x16x32_bf16 v[12:15], v[136:139], v[232:235], v[12:15]
	v_mfma_f32_16x16x32_bf16 v[16:19], v[116:119], v[228:231], v[16:19]
	v_mfma_f32_16x16x32_bf16 v[16:19], v[120:123], v[232:235], v[16:19]
	v_mfma_f32_16x16x32_bf16 v[56:59], v[148:151], v[190:193], v[56:59]
	v_mfma_f32_16x16x32_bf16 v[56:59], v[152:155], v[194:197], v[56:59]
	v_mfma_f32_16x16x32_bf16 v[52:55], v[182:185], v[190:193], v[52:55]
	v_mfma_f32_16x16x32_bf16 v[52:55], v[186:189], v[194:197], v[52:55]
	v_mfma_f32_16x16x32_bf16 v[36:39], v[182:185], v[204:207], v[36:39]
	v_mfma_f32_16x16x32_bf16 v[36:39], v[186:189], v[208:211], v[36:39]
	v_mfma_f32_16x16x32_bf16 v[40:43], v[148:151], v[204:207], v[40:43]
	v_mfma_f32_16x16x32_bf16 v[40:43], v[152:155], v[208:211], v[40:43]
	v_mfma_f32_16x16x32_bf16 v[24:27], v[148:151], v[212:215], v[24:27]
	v_mfma_f32_16x16x32_bf16 v[24:27], v[152:155], v[216:219], v[24:27]
	v_mfma_f32_16x16x32_bf16 v[20:23], v[182:185], v[212:215], v[20:23]
	v_mfma_f32_16x16x32_bf16 v[20:23], v[186:189], v[216:219], v[20:23]
	v_mfma_f32_16x16x32_bf16 v[4:7], v[182:185], v[228:231], v[4:7]
	v_mfma_f32_16x16x32_bf16 v[4:7], v[186:189], v[232:235], v[4:7]
	v_mfma_f32_16x16x32_bf16 v[8:11], v[148:151], v[228:231], v[8:11]
	v_mfma_f32_16x16x32_bf16 v[8:11], v[152:155], v[232:235], v[8:11]
	s_setprio 0
	s_barrier
	s_add_u32 s49, s49, 0x80000
	s_addc_u32 s97, s97, 0
	s_add_u32 s42, s42, 0x100
	s_addc_u32 s43, s43, 0
	s_cmp_ge_u32 vcc_lo, s69
	s_mov_b32 s34, vcc_lo
	s_cbranch_scc0 .Ltrail_3
.Lkdone_3:
	s_and_b64 vcc, exec, s[46:47]
	s_cbranch_vccz .LBB0_562
	s_barrier
